# all validated edits combined: att softmax+output, sel canon/pipeline/atomic/prefetch, WIN fast epilogue, gate stats, prologue loads
# speedup vs baseline: 1.0074x; 1.0074x over previous
.LBB0_92:
	s_or_b64 exec, exec, s[14:15]
	v_lshl_add_u64 v[22:23], v[14:15], 0, v[10:11]
	global_load_dwordx4 v[18:21], v[22:23], off
	global_load_dwordx4 v[26:29], v[22:23], off offset:1024
	global_load_dwordx4 v[30:33], v[22:23], off offset:2048
	global_load_dwordx4 v[34:37], v[22:23], off offset:3072
	v_lshlrev_b64 v[14:15], 11, v[16:17]
	v_lshl_add_u64 v[24:25], v[6:7], 0, v[14:15]
	v_lshl_add_u64 v[12:13], v[12:13], 0, s[30:31]
	v_cmp_lt_i32_e32 vcc, s16, v12
	s_or_b64 s[12:13], vcc, s[12:13]
	v_lshl_add_u64 v[8:9], v[8:9], 0, s[6:7]
	s_waitcnt vmcnt(3)
	v_cvt_pk_bf16_f32 v14, v18, v19
	v_cvt_pk_bf16_f32 v15, v20, v21
	global_store_dwordx2 v[24:25], v[14:15], off
	s_waitcnt vmcnt(3)
	v_cvt_pk_bf16_f32 v38, v26, v27
	v_cvt_pk_bf16_f32 v39, v28, v29
	global_store_dwordx2 v[24:25], v[38:39], off offset:512
	s_waitcnt vmcnt(3)
	v_cvt_pk_bf16_f32 v40, v30, v31
	v_cvt_pk_bf16_f32 v41, v32, v33
	global_store_dwordx2 v[24:25], v[40:41], off offset:1024
	s_waitcnt vmcnt(3)
	v_cvt_pk_bf16_f32 v42, v34, v35
	v_cvt_pk_bf16_f32 v43, v36, v37
	global_store_dwordx2 v[24:25], v[42:43], off offset:1536
	s_andn2_b64 exec, exec, s[12:13]
	s_cbranch_execz .LBB0_97

.LBB0_99:
	s_waitcnt lgkmcnt(0)
	v_lshl_add_u64 v[8:9], s[4:5], 0, v[6:7]
	v_lshl_add_u64 v[12:13], s[6:7], 0, v[6:7]
	global_load_dwordx4 v[8:11], v[8:9], off
	global_load_dwordx4 v[26:29], v[12:13], off
	v_ashrrev_i32_e32 v14, 10, v3
	v_and_b32_e32 v4, 0x3ff, v3
	v_mul_hi_i32_i24_e32 v15, 0x410, v14
	v_mul_i32_i24_e32 v14, 0x410, v14
	v_lshl_add_u64 v[14:15], v[14:15], 0, v[4:5]
	v_lshlrev_b64 v[14:15], 9, v[14:15]
	v_lshl_or_b32 v14, v2, 1, v14
	v_lshl_add_u64 v[16:17], s[14:15], 0, v[14:15]
	v_lshl_add_u64 v[12:13], s[16:17], 0, v[14:15]
	v_add_u32_e32 v3, s30, v3
	v_cmp_lt_i32_e32 vcc, s3, v3
	v_lshl_add_u64 v[6:7], v[6:7], 0, s[18:19]
	s_or_b64 s[20:21], vcc, s[20:21]
	s_waitcnt vmcnt(1)
	v_cvt_pk_bf16_f32 v8, v8, v9
	v_cvt_pk_bf16_f32 v9, v10, v11
	global_store_dwordx2 v[16:17], v[8:9], off
	s_waitcnt vmcnt(1)
	v_cvt_pk_bf16_f32 v30, v26, v27
	v_cvt_pk_bf16_f32 v31, v28, v29
	global_store_dwordx2 v[12:13], v[30:31], off
	s_andn2_b64 exec, exec, s[20:21]
	s_cbranch_execnz .LBB0_99

.LBB0_374:
	s_cmp_eq_u32 s12, 4
	s_cbranch_scc1 .Lwin_slow
	s_cmp_eq_u32 s12, 5
	s_cbranch_scc1 .Lwin_slow
	s_cmp_eq_u32 s12, 8
	s_cbranch_scc1 .Lwin_slow
	s_mov_b32 s13, 11
	s_mov_b64 s[56:57], s[22:23]
	s_cmp_lt_u32 s12, 4
	s_cbranch_scc1 .Lwin_c_q
	s_cmp_lt_u32 s12, 8
	s_cbranch_scc1 .Lwin_c_qi
	s_cmp_lt_u32 s12, 13
	s_cbranch_scc1 .Lwin_c_u
	s_cmp_lt_u32 s12, 17
	s_cbranch_scc1 .Lwin_c_v
	s_mov_b64 s[56:57], s[20:21]
	s_cmp_lt_u32 s12, 21
	s_cbranch_scc1 .Lwin_c_ga
	s_sub_i32 s60, s12, 21
	s_mov_b32 s61, 0x8100000
	s_mov_b32 s16, 2
	s_branch .Lwin_c_done
.Lwin_c_ga:
	s_sub_i32 s60, s12, 17
	s_mov_b32 s61, 0x0
	s_mov_b32 s16, 2
	s_branch .Lwin_c_done
.Lwin_c_v:
	s_sub_i32 s60, s12, 13
	s_mov_b32 s61, 0x26c00000
	s_mov_b32 s16, 1
	s_branch .Lwin_c_done
.Lwin_c_u:
	s_sub_i32 s60, s12, 9
	s_mov_b32 s61, 0x1eb00000
	s_mov_b32 s16, 1
	s_branch .Lwin_c_done
.Lwin_c_qi:
	s_sub_i32 s60, s12, 6
	s_mov_b32 s61, 0x2ed00000
	s_mov_b32 s16, 0
	s_mov_b32 s13, 10
	s_branch .Lwin_c_done
.Lwin_c_q:
	s_sub_i32 s60, s12, 0
	s_mov_b32 s61, 0x16a00000
	s_mov_b32 s16, 0
	s_branch .Lwin_c_done
.Lwin_c_done:
	s_lshl_b32 s60, s60, 9
	s_add_u32 s56, s56, s61
	s_addc_u32 s57, s57, 0
	s_add_u32 s56, s56, s60
	s_addc_u32 s57, s57, 0
	s_lshl_b32 s60, s14, 8
	s_lshl_b32 s60, s60, s13
	s_add_u32 s60, s56, s60
	s_addc_u32 s61, s57, 0
	s_mov_b32 s64, 16
	s_lshl_b32 s64, s64, s13
	s_lshl_b32 s65, s64, 2
	v_lshlrev_b32_e32 v174, s13, v149
	v_lshl_add_u32 v174, v146, 1, v174
	s_cmp_eq_u32 s16, 1
	s_cbranch_scc1 .Lwin_act1
	s_cmp_eq_u32 s16, 2
	s_cbranch_scc1 .Lwin_act2
	v_cvt_pk_bf16_f32 v128, v124, v125
	v_cvt_pk_bf16_f32 v129, v126, v127
	v_cvt_pk_bf16_f32 v130, v120, v121
	v_cvt_pk_bf16_f32 v131, v122, v123
	global_store_dwordx4 v174, v[128:131], s[60:61]
	v_cvt_pk_bf16_f32 v120, v116, v117
	v_cvt_pk_bf16_f32 v121, v118, v119
	v_cvt_pk_bf16_f32 v122, v112, v113
	v_cvt_pk_bf16_f32 v123, v114, v115
	global_store_dwordx4 v174, v[120:123], s[60:61] offset:256
	s_add_u32 s60, s60, s64
	s_addc_u32 s61, s61, 0
	v_cvt_pk_bf16_f32 v112, v108, v109
	v_cvt_pk_bf16_f32 v113, v110, v111
	v_cvt_pk_bf16_f32 v114, v104, v105
	v_cvt_pk_bf16_f32 v115, v106, v107
	global_store_dwordx4 v174, v[112:115], s[60:61]
	v_cvt_pk_bf16_f32 v104, v100, v101
	v_cvt_pk_bf16_f32 v105, v102, v103
	v_cvt_pk_bf16_f32 v106, v96, v97
	v_cvt_pk_bf16_f32 v107, v98, v99
	global_store_dwordx4 v174, v[104:107], s[60:61] offset:256
	s_add_u32 s60, s60, s64
	s_addc_u32 s61, s61, 0
	v_cvt_pk_bf16_f32 v96, v92, v93
	v_cvt_pk_bf16_f32 v97, v94, v95
	v_cvt_pk_bf16_f32 v98, v88, v89
	v_cvt_pk_bf16_f32 v99, v90, v91
	global_store_dwordx4 v174, v[96:99], s[60:61]
	v_cvt_pk_bf16_f32 v88, v84, v85
	v_cvt_pk_bf16_f32 v89, v86, v87
	v_cvt_pk_bf16_f32 v90, v80, v81
	v_cvt_pk_bf16_f32 v91, v82, v83
	global_store_dwordx4 v174, v[88:91], s[60:61] offset:256
	s_add_u32 s60, s60, s64
	s_addc_u32 s61, s61, 0
	v_cvt_pk_bf16_f32 v80, v76, v77
	v_cvt_pk_bf16_f32 v81, v78, v79
	v_cvt_pk_bf16_f32 v82, v72, v73
	v_cvt_pk_bf16_f32 v83, v74, v75
	global_store_dwordx4 v174, v[80:83], s[60:61]
	v_cvt_pk_bf16_f32 v72, v68, v69
	v_cvt_pk_bf16_f32 v73, v70, v71
	v_cvt_pk_bf16_f32 v74, v64, v65
	v_cvt_pk_bf16_f32 v75, v66, v67
	global_store_dwordx4 v174, v[72:75], s[60:61] offset:256
	s_add_u32 s60, s60, s64
	s_addc_u32 s61, s61, 0
	s_add_u32 s60, s60, s65
	s_addc_u32 s61, s61, 0
	v_cvt_pk_bf16_f32 v64, v60, v61
	v_cvt_pk_bf16_f32 v65, v62, v63
	v_cvt_pk_bf16_f32 v66, v56, v57
	v_cvt_pk_bf16_f32 v67, v58, v59
	global_store_dwordx4 v174, v[64:67], s[60:61]
	v_cvt_pk_bf16_f32 v56, v52, v53
	v_cvt_pk_bf16_f32 v57, v54, v55
	v_cvt_pk_bf16_f32 v58, v48, v49
	v_cvt_pk_bf16_f32 v59, v50, v51
	global_store_dwordx4 v174, v[56:59], s[60:61] offset:256
	s_add_u32 s60, s60, s64
	s_addc_u32 s61, s61, 0
	v_cvt_pk_bf16_f32 v48, v44, v45
	v_cvt_pk_bf16_f32 v49, v46, v47
	v_cvt_pk_bf16_f32 v50, v40, v41
	v_cvt_pk_bf16_f32 v51, v42, v43
	global_store_dwordx4 v174, v[48:51], s[60:61]
	v_cvt_pk_bf16_f32 v40, v36, v37
	v_cvt_pk_bf16_f32 v41, v38, v39
	v_cvt_pk_bf16_f32 v42, v32, v33
	v_cvt_pk_bf16_f32 v43, v34, v35
	global_store_dwordx4 v174, v[40:43], s[60:61] offset:256
	s_add_u32 s60, s60, s64
	s_addc_u32 s61, s61, 0
	v_cvt_pk_bf16_f32 v32, v28, v29
	v_cvt_pk_bf16_f32 v33, v30, v31
	v_cvt_pk_bf16_f32 v34, v24, v25
	v_cvt_pk_bf16_f32 v35, v26, v27
	global_store_dwordx4 v174, v[32:35], s[60:61]
	v_cvt_pk_bf16_f32 v24, v20, v21
	v_cvt_pk_bf16_f32 v25, v22, v23
	v_cvt_pk_bf16_f32 v26, v16, v17
	v_cvt_pk_bf16_f32 v27, v18, v19
	global_store_dwordx4 v174, v[24:27], s[60:61] offset:256
	s_add_u32 s60, s60, s64
	s_addc_u32 s61, s61, 0
	v_cvt_pk_bf16_f32 v16, v12, v13
	v_cvt_pk_bf16_f32 v17, v14, v15
	v_cvt_pk_bf16_f32 v18, v8, v9
	v_cvt_pk_bf16_f32 v19, v10, v11
	global_store_dwordx4 v174, v[16:19], s[60:61]
	v_cvt_pk_bf16_f32 v8, v4, v5
	v_cvt_pk_bf16_f32 v9, v6, v7
	v_cvt_pk_bf16_f32 v10, v0, v1
	v_cvt_pk_bf16_f32 v11, v2, v3
	global_store_dwordx4 v174, v[8:11], s[60:61] offset:256
	s_branch .Lwin_done
.Lwin_act1:
	v_mul_f32_e32 v128, 0x3d372713, v124
	v_mul_f32_e32 v129, 0x3d372713, v125
	v_mul_f32_e32 v130, 0x3d372713, v126
	v_mul_f32_e32 v131, 0x3d372713, v127
	v_mul_f32_e32 v132, 0x3d372713, v120
	v_mul_f32_e32 v133, 0x3d372713, v121
	v_mul_f32_e32 v134, 0x3d372713, v122
	v_mul_f32_e32 v135, 0x3d372713, v123
	v_mul_f32_e32 v128, v124, v128
	v_mul_f32_e32 v129, v125, v129
	v_mul_f32_e32 v130, v126, v130
	v_mul_f32_e32 v131, v127, v131
	v_mul_f32_e32 v132, v120, v132
	v_mul_f32_e32 v133, v121, v133
	v_mul_f32_e32 v134, v122, v134
	v_mul_f32_e32 v135, v123, v135
	v_fma_f32 v128, v124, v128, v124
	v_fma_f32 v129, v125, v129, v125
	v_fma_f32 v130, v126, v130, v126
	v_fma_f32 v131, v127, v131, v127
	v_fma_f32 v132, v120, v132, v120
	v_fma_f32 v133, v121, v133, v121
	v_fma_f32 v134, v122, v134, v122
	v_fma_f32 v135, v123, v135, v123
	v_mul_f32_e32 v128, 0x3fcc422a, v128
	v_mul_f32_e32 v129, 0x3fcc422a, v129
	v_mul_f32_e32 v130, 0x3fcc422a, v130
	v_mul_f32_e32 v131, 0x3fcc422a, v131
	v_mul_f32_e32 v132, 0x3fcc422a, v132
	v_mul_f32_e32 v133, 0x3fcc422a, v133
	v_mul_f32_e32 v134, 0x3fcc422a, v134
	v_mul_f32_e32 v135, 0x3fcc422a, v135
	v_mul_f32_e32 v128, 0xbfb8aa3b, v128
	v_mul_f32_e32 v129, 0xbfb8aa3b, v129
	v_mul_f32_e32 v130, 0xbfb8aa3b, v130
	v_mul_f32_e32 v131, 0xbfb8aa3b, v131
	v_mul_f32_e32 v132, 0xbfb8aa3b, v132
	v_mul_f32_e32 v133, 0xbfb8aa3b, v133
	v_mul_f32_e32 v134, 0xbfb8aa3b, v134
	v_mul_f32_e32 v135, 0xbfb8aa3b, v135
	v_exp_f32_e32 v128, v128
	v_exp_f32_e32 v129, v129
	v_exp_f32_e32 v130, v130
	v_exp_f32_e32 v131, v131
	v_exp_f32_e32 v132, v132
	v_exp_f32_e32 v133, v133
	v_exp_f32_e32 v134, v134
	v_exp_f32_e32 v135, v135
	v_add_f32_e32 v128, 1.0, v128
	v_add_f32_e32 v129, 1.0, v129
	v_add_f32_e32 v130, 1.0, v130
	v_add_f32_e32 v131, 1.0, v131
	v_add_f32_e32 v132, 1.0, v132
	v_add_f32_e32 v133, 1.0, v133
	v_add_f32_e32 v134, 1.0, v134
	v_add_f32_e32 v135, 1.0, v135
	v_rcp_f32_e32 v128, v128
	v_rcp_f32_e32 v129, v129
	v_rcp_f32_e32 v130, v130
	v_rcp_f32_e32 v131, v131
	v_rcp_f32_e32 v132, v132
	v_rcp_f32_e32 v133, v133
	v_rcp_f32_e32 v134, v134
	v_rcp_f32_e32 v135, v135
	v_mul_f32_e32 v128, v124, v128
	v_mul_f32_e32 v129, v125, v129
	v_mul_f32_e32 v130, v126, v130
	v_mul_f32_e32 v131, v127, v131
	v_mul_f32_e32 v132, v120, v132
	v_mul_f32_e32 v133, v121, v133
	v_mul_f32_e32 v134, v122, v134
	v_mul_f32_e32 v135, v123, v135
	v_cvt_pk_bf16_f32 v128, v128, v129
	v_cvt_pk_bf16_f32 v129, v130, v131
	v_cvt_pk_bf16_f32 v130, v132, v133
	v_cvt_pk_bf16_f32 v131, v134, v135
	global_store_dwordx4 v174, v[128:131], s[60:61]
	v_mul_f32_e32 v120, 0x3d372713, v116
	v_mul_f32_e32 v121, 0x3d372713, v117
	v_mul_f32_e32 v122, 0x3d372713, v118
	v_mul_f32_e32 v123, 0x3d372713, v119
	v_mul_f32_e32 v124, 0x3d372713, v112
	v_mul_f32_e32 v125, 0x3d372713, v113
	v_mul_f32_e32 v126, 0x3d372713, v114
	v_mul_f32_e32 v127, 0x3d372713, v115
	v_mul_f32_e32 v120, v116, v120
	v_mul_f32_e32 v121, v117, v121
	v_mul_f32_e32 v122, v118, v122
	v_mul_f32_e32 v123, v119, v123
	v_mul_f32_e32 v124, v112, v124
	v_mul_f32_e32 v125, v113, v125
	v_mul_f32_e32 v126, v114, v126
	v_mul_f32_e32 v127, v115, v127
	v_fma_f32 v120, v116, v120, v116
	v_fma_f32 v121, v117, v121, v117
	v_fma_f32 v122, v118, v122, v118
	v_fma_f32 v123, v119, v123, v119
	v_fma_f32 v124, v112, v124, v112
	v_fma_f32 v125, v113, v125, v113
	v_fma_f32 v126, v114, v126, v114
	v_fma_f32 v127, v115, v127, v115
	v_mul_f32_e32 v120, 0x3fcc422a, v120
	v_mul_f32_e32 v121, 0x3fcc422a, v121
	v_mul_f32_e32 v122, 0x3fcc422a, v122
	v_mul_f32_e32 v123, 0x3fcc422a, v123
	v_mul_f32_e32 v124, 0x3fcc422a, v124
	v_mul_f32_e32 v125, 0x3fcc422a, v125
	v_mul_f32_e32 v126, 0x3fcc422a, v126
	v_mul_f32_e32 v127, 0x3fcc422a, v127
	v_mul_f32_e32 v120, 0xbfb8aa3b, v120
	v_mul_f32_e32 v121, 0xbfb8aa3b, v121
	v_mul_f32_e32 v122, 0xbfb8aa3b, v122
	v_mul_f32_e32 v123, 0xbfb8aa3b, v123
	v_mul_f32_e32 v124, 0xbfb8aa3b, v124
	v_mul_f32_e32 v125, 0xbfb8aa3b, v125
	v_mul_f32_e32 v126, 0xbfb8aa3b, v126
	v_mul_f32_e32 v127, 0xbfb8aa3b, v127
	v_exp_f32_e32 v120, v120
	v_exp_f32_e32 v121, v121
	v_exp_f32_e32 v122, v122
	v_exp_f32_e32 v123, v123
	v_exp_f32_e32 v124, v124
	v_exp_f32_e32 v125, v125
	v_exp_f32_e32 v126, v126
	v_exp_f32_e32 v127, v127
	v_add_f32_e32 v120, 1.0, v120
	v_add_f32_e32 v121, 1.0, v121
	v_add_f32_e32 v122, 1.0, v122
	v_add_f32_e32 v123, 1.0, v123
	v_add_f32_e32 v124, 1.0, v124
	v_add_f32_e32 v125, 1.0, v125
	v_add_f32_e32 v126, 1.0, v126
	v_add_f32_e32 v127, 1.0, v127
	v_rcp_f32_e32 v120, v120
	v_rcp_f32_e32 v121, v121
	v_rcp_f32_e32 v122, v122
	v_rcp_f32_e32 v123, v123
	v_rcp_f32_e32 v124, v124
	v_rcp_f32_e32 v125, v125
	v_rcp_f32_e32 v126, v126
	v_rcp_f32_e32 v127, v127
	v_mul_f32_e32 v120, v116, v120
	v_mul_f32_e32 v121, v117, v121
	v_mul_f32_e32 v122, v118, v122
	v_mul_f32_e32 v123, v119, v123
	v_mul_f32_e32 v124, v112, v124
	v_mul_f32_e32 v125, v113, v125
	v_mul_f32_e32 v126, v114, v126
	v_mul_f32_e32 v127, v115, v127
	v_cvt_pk_bf16_f32 v120, v120, v121
	v_cvt_pk_bf16_f32 v121, v122, v123
	v_cvt_pk_bf16_f32 v122, v124, v125
	v_cvt_pk_bf16_f32 v123, v126, v127
	global_store_dwordx4 v174, v[120:123], s[60:61] offset:256
	s_add_u32 s60, s60, s64
	s_addc_u32 s61, s61, 0
	v_mul_f32_e32 v112, 0x3d372713, v108
	v_mul_f32_e32 v113, 0x3d372713, v109
	v_mul_f32_e32 v114, 0x3d372713, v110
	v_mul_f32_e32 v115, 0x3d372713, v111
	v_mul_f32_e32 v116, 0x3d372713, v104
	v_mul_f32_e32 v117, 0x3d372713, v105
	v_mul_f32_e32 v118, 0x3d372713, v106
	v_mul_f32_e32 v119, 0x3d372713, v107
	v_mul_f32_e32 v112, v108, v112
	v_mul_f32_e32 v113, v109, v113
	v_mul_f32_e32 v114, v110, v114
	v_mul_f32_e32 v115, v111, v115
	v_mul_f32_e32 v116, v104, v116
	v_mul_f32_e32 v117, v105, v117
	v_mul_f32_e32 v118, v106, v118
	v_mul_f32_e32 v119, v107, v119
	v_fma_f32 v112, v108, v112, v108
	v_fma_f32 v113, v109, v113, v109
	v_fma_f32 v114, v110, v114, v110
	v_fma_f32 v115, v111, v115, v111
	v_fma_f32 v116, v104, v116, v104
	v_fma_f32 v117, v105, v117, v105
	v_fma_f32 v118, v106, v118, v106
	v_fma_f32 v119, v107, v119, v107
	v_mul_f32_e32 v112, 0x3fcc422a, v112
	v_mul_f32_e32 v113, 0x3fcc422a, v113
	v_mul_f32_e32 v114, 0x3fcc422a, v114
	v_mul_f32_e32 v115, 0x3fcc422a, v115
	v_mul_f32_e32 v116, 0x3fcc422a, v116
	v_mul_f32_e32 v117, 0x3fcc422a, v117
	v_mul_f32_e32 v118, 0x3fcc422a, v118
	v_mul_f32_e32 v119, 0x3fcc422a, v119
	v_mul_f32_e32 v112, 0xbfb8aa3b, v112
	v_mul_f32_e32 v113, 0xbfb8aa3b, v113
	v_mul_f32_e32 v114, 0xbfb8aa3b, v114
	v_mul_f32_e32 v115, 0xbfb8aa3b, v115
	v_mul_f32_e32 v116, 0xbfb8aa3b, v116
	v_mul_f32_e32 v117, 0xbfb8aa3b, v117
	v_mul_f32_e32 v118, 0xbfb8aa3b, v118
	v_mul_f32_e32 v119, 0xbfb8aa3b, v119
	v_exp_f32_e32 v112, v112
	v_exp_f32_e32 v113, v113
	v_exp_f32_e32 v114, v114
	v_exp_f32_e32 v115, v115
	v_exp_f32_e32 v116, v116
	v_exp_f32_e32 v117, v117
	v_exp_f32_e32 v118, v118
	v_exp_f32_e32 v119, v119
	v_add_f32_e32 v112, 1.0, v112
	v_add_f32_e32 v113, 1.0, v113
	v_add_f32_e32 v114, 1.0, v114
	v_add_f32_e32 v115, 1.0, v115
	v_add_f32_e32 v116, 1.0, v116
	v_add_f32_e32 v117, 1.0, v117
	v_add_f32_e32 v118, 1.0, v118
	v_add_f32_e32 v119, 1.0, v119
	v_rcp_f32_e32 v112, v112
	v_rcp_f32_e32 v113, v113
	v_rcp_f32_e32 v114, v114
	v_rcp_f32_e32 v115, v115
	v_rcp_f32_e32 v116, v116
	v_rcp_f32_e32 v117, v117
	v_rcp_f32_e32 v118, v118
	v_rcp_f32_e32 v119, v119
	v_mul_f32_e32 v112, v108, v112
	v_mul_f32_e32 v113, v109, v113
	v_mul_f32_e32 v114, v110, v114
	v_mul_f32_e32 v115, v111, v115
	v_mul_f32_e32 v116, v104, v116
	v_mul_f32_e32 v117, v105, v117
	v_mul_f32_e32 v118, v106, v118
	v_mul_f32_e32 v119, v107, v119
	v_cvt_pk_bf16_f32 v112, v112, v113
	v_cvt_pk_bf16_f32 v113, v114, v115
	v_cvt_pk_bf16_f32 v114, v116, v117
	v_cvt_pk_bf16_f32 v115, v118, v119
	global_store_dwordx4 v174, v[112:115], s[60:61]
	v_mul_f32_e32 v104, 0x3d372713, v100
	v_mul_f32_e32 v105, 0x3d372713, v101
	v_mul_f32_e32 v106, 0x3d372713, v102
	v_mul_f32_e32 v107, 0x3d372713, v103
	v_mul_f32_e32 v108, 0x3d372713, v96
	v_mul_f32_e32 v109, 0x3d372713, v97
	v_mul_f32_e32 v110, 0x3d372713, v98
	v_mul_f32_e32 v111, 0x3d372713, v99
	v_mul_f32_e32 v104, v100, v104
	v_mul_f32_e32 v105, v101, v105
	v_mul_f32_e32 v106, v102, v106
	v_mul_f32_e32 v107, v103, v107
	v_mul_f32_e32 v108, v96, v108
	v_mul_f32_e32 v109, v97, v109
	v_mul_f32_e32 v110, v98, v110
	v_mul_f32_e32 v111, v99, v111
	v_fma_f32 v104, v100, v104, v100
	v_fma_f32 v105, v101, v105, v101
	v_fma_f32 v106, v102, v106, v102
	v_fma_f32 v107, v103, v107, v103
	v_fma_f32 v108, v96, v108, v96
	v_fma_f32 v109, v97, v109, v97
	v_fma_f32 v110, v98, v110, v98
	v_fma_f32 v111, v99, v111, v99
	v_mul_f32_e32 v104, 0x3fcc422a, v104
	v_mul_f32_e32 v105, 0x3fcc422a, v105
	v_mul_f32_e32 v106, 0x3fcc422a, v106
	v_mul_f32_e32 v107, 0x3fcc422a, v107
	v_mul_f32_e32 v108, 0x3fcc422a, v108
	v_mul_f32_e32 v109, 0x3fcc422a, v109
	v_mul_f32_e32 v110, 0x3fcc422a, v110
	v_mul_f32_e32 v111, 0x3fcc422a, v111
	v_mul_f32_e32 v104, 0xbfb8aa3b, v104
	v_mul_f32_e32 v105, 0xbfb8aa3b, v105
	v_mul_f32_e32 v106, 0xbfb8aa3b, v106
	v_mul_f32_e32 v107, 0xbfb8aa3b, v107
	v_mul_f32_e32 v108, 0xbfb8aa3b, v108
	v_mul_f32_e32 v109, 0xbfb8aa3b, v109
	v_mul_f32_e32 v110, 0xbfb8aa3b, v110
	v_mul_f32_e32 v111, 0xbfb8aa3b, v111
	v_exp_f32_e32 v104, v104
	v_exp_f32_e32 v105, v105
	v_exp_f32_e32 v106, v106
	v_exp_f32_e32 v107, v107
	v_exp_f32_e32 v108, v108
	v_exp_f32_e32 v109, v109
	v_exp_f32_e32 v110, v110
	v_exp_f32_e32 v111, v111
	v_add_f32_e32 v104, 1.0, v104
	v_add_f32_e32 v105, 1.0, v105
	v_add_f32_e32 v106, 1.0, v106
	v_add_f32_e32 v107, 1.0, v107
	v_add_f32_e32 v108, 1.0, v108
	v_add_f32_e32 v109, 1.0, v109
	v_add_f32_e32 v110, 1.0, v110
	v_add_f32_e32 v111, 1.0, v111
	v_rcp_f32_e32 v104, v104
	v_rcp_f32_e32 v105, v105
	v_rcp_f32_e32 v106, v106
	v_rcp_f32_e32 v107, v107
	v_rcp_f32_e32 v108, v108
	v_rcp_f32_e32 v109, v109
	v_rcp_f32_e32 v110, v110
	v_rcp_f32_e32 v111, v111
	v_mul_f32_e32 v104, v100, v104
	v_mul_f32_e32 v105, v101, v105
	v_mul_f32_e32 v106, v102, v106
	v_mul_f32_e32 v107, v103, v107
	v_mul_f32_e32 v108, v96, v108
	v_mul_f32_e32 v109, v97, v109
	v_mul_f32_e32 v110, v98, v110
	v_mul_f32_e32 v111, v99, v111
	v_cvt_pk_bf16_f32 v104, v104, v105
	v_cvt_pk_bf16_f32 v105, v106, v107
	v_cvt_pk_bf16_f32 v106, v108, v109
	v_cvt_pk_bf16_f32 v107, v110, v111
	global_store_dwordx4 v174, v[104:107], s[60:61] offset:256
	s_add_u32 s60, s60, s64
	s_addc_u32 s61, s61, 0
	v_mul_f32_e32 v96, 0x3d372713, v92
	v_mul_f32_e32 v97, 0x3d372713, v93
	v_mul_f32_e32 v98, 0x3d372713, v94
	v_mul_f32_e32 v99, 0x3d372713, v95
	v_mul_f32_e32 v100, 0x3d372713, v88
	v_mul_f32_e32 v101, 0x3d372713, v89
	v_mul_f32_e32 v102, 0x3d372713, v90
	v_mul_f32_e32 v103, 0x3d372713, v91
	v_mul_f32_e32 v96, v92, v96
	v_mul_f32_e32 v97, v93, v97
	v_mul_f32_e32 v98, v94, v98
	v_mul_f32_e32 v99, v95, v99
	v_mul_f32_e32 v100, v88, v100
	v_mul_f32_e32 v101, v89, v101
	v_mul_f32_e32 v102, v90, v102
	v_mul_f32_e32 v103, v91, v103
	v_fma_f32 v96, v92, v96, v92
	v_fma_f32 v97, v93, v97, v93
	v_fma_f32 v98, v94, v98, v94
	v_fma_f32 v99, v95, v99, v95
	v_fma_f32 v100, v88, v100, v88
	v_fma_f32 v101, v89, v101, v89
	v_fma_f32 v102, v90, v102, v90
	v_fma_f32 v103, v91, v103, v91
	v_mul_f32_e32 v96, 0x3fcc422a, v96
	v_mul_f32_e32 v97, 0x3fcc422a, v97
	v_mul_f32_e32 v98, 0x3fcc422a, v98
	v_mul_f32_e32 v99, 0x3fcc422a, v99
	v_mul_f32_e32 v100, 0x3fcc422a, v100
	v_mul_f32_e32 v101, 0x3fcc422a, v101
	v_mul_f32_e32 v102, 0x3fcc422a, v102
	v_mul_f32_e32 v103, 0x3fcc422a, v103
	v_mul_f32_e32 v96, 0xbfb8aa3b, v96
	v_mul_f32_e32 v97, 0xbfb8aa3b, v97
	v_mul_f32_e32 v98, 0xbfb8aa3b, v98
	v_mul_f32_e32 v99, 0xbfb8aa3b, v99
	v_mul_f32_e32 v100, 0xbfb8aa3b, v100
	v_mul_f32_e32 v101, 0xbfb8aa3b, v101
	v_mul_f32_e32 v102, 0xbfb8aa3b, v102
	v_mul_f32_e32 v103, 0xbfb8aa3b, v103
	v_exp_f32_e32 v96, v96
	v_exp_f32_e32 v97, v97
	v_exp_f32_e32 v98, v98
	v_exp_f32_e32 v99, v99
	v_exp_f32_e32 v100, v100
	v_exp_f32_e32 v101, v101
	v_exp_f32_e32 v102, v102
	v_exp_f32_e32 v103, v103
	v_add_f32_e32 v96, 1.0, v96
	v_add_f32_e32 v97, 1.0, v97
	v_add_f32_e32 v98, 1.0, v98
	v_add_f32_e32 v99, 1.0, v99
	v_add_f32_e32 v100, 1.0, v100
	v_add_f32_e32 v101, 1.0, v101
	v_add_f32_e32 v102, 1.0, v102
	v_add_f32_e32 v103, 1.0, v103
	v_rcp_f32_e32 v96, v96
	v_rcp_f32_e32 v97, v97
	v_rcp_f32_e32 v98, v98
	v_rcp_f32_e32 v99, v99
	v_rcp_f32_e32 v100, v100
	v_rcp_f32_e32 v101, v101
	v_rcp_f32_e32 v102, v102
	v_rcp_f32_e32 v103, v103
	v_mul_f32_e32 v96, v92, v96
	v_mul_f32_e32 v97, v93, v97
	v_mul_f32_e32 v98, v94, v98
	v_mul_f32_e32 v99, v95, v99
	v_mul_f32_e32 v100, v88, v100
	v_mul_f32_e32 v101, v89, v101
	v_mul_f32_e32 v102, v90, v102
	v_mul_f32_e32 v103, v91, v103
	v_cvt_pk_bf16_f32 v96, v96, v97
	v_cvt_pk_bf16_f32 v97, v98, v99
	v_cvt_pk_bf16_f32 v98, v100, v101
	v_cvt_pk_bf16_f32 v99, v102, v103
	global_store_dwordx4 v174, v[96:99], s[60:61]
	v_mul_f32_e32 v88, 0x3d372713, v84
	v_mul_f32_e32 v89, 0x3d372713, v85
	v_mul_f32_e32 v90, 0x3d372713, v86
	v_mul_f32_e32 v91, 0x3d372713, v87
	v_mul_f32_e32 v92, 0x3d372713, v80
	v_mul_f32_e32 v93, 0x3d372713, v81
	v_mul_f32_e32 v94, 0x3d372713, v82
	v_mul_f32_e32 v95, 0x3d372713, v83
	v_mul_f32_e32 v88, v84, v88
	v_mul_f32_e32 v89, v85, v89
	v_mul_f32_e32 v90, v86, v90
	v_mul_f32_e32 v91, v87, v91
	v_mul_f32_e32 v92, v80, v92
	v_mul_f32_e32 v93, v81, v93
	v_mul_f32_e32 v94, v82, v94
	v_mul_f32_e32 v95, v83, v95
	v_fma_f32 v88, v84, v88, v84
	v_fma_f32 v89, v85, v89, v85
	v_fma_f32 v90, v86, v90, v86
	v_fma_f32 v91, v87, v91, v87
	v_fma_f32 v92, v80, v92, v80
	v_fma_f32 v93, v81, v93, v81
	v_fma_f32 v94, v82, v94, v82
	v_fma_f32 v95, v83, v95, v83
	v_mul_f32_e32 v88, 0x3fcc422a, v88
	v_mul_f32_e32 v89, 0x3fcc422a, v89
	v_mul_f32_e32 v90, 0x3fcc422a, v90
	v_mul_f32_e32 v91, 0x3fcc422a, v91
	v_mul_f32_e32 v92, 0x3fcc422a, v92
	v_mul_f32_e32 v93, 0x3fcc422a, v93
	v_mul_f32_e32 v94, 0x3fcc422a, v94
	v_mul_f32_e32 v95, 0x3fcc422a, v95
	v_mul_f32_e32 v88, 0xbfb8aa3b, v88
	v_mul_f32_e32 v89, 0xbfb8aa3b, v89
	v_mul_f32_e32 v90, 0xbfb8aa3b, v90
	v_mul_f32_e32 v91, 0xbfb8aa3b, v91
	v_mul_f32_e32 v92, 0xbfb8aa3b, v92
	v_mul_f32_e32 v93, 0xbfb8aa3b, v93
	v_mul_f32_e32 v94, 0xbfb8aa3b, v94
	v_mul_f32_e32 v95, 0xbfb8aa3b, v95
	v_exp_f32_e32 v88, v88
	v_exp_f32_e32 v89, v89
	v_exp_f32_e32 v90, v90
	v_exp_f32_e32 v91, v91
	v_exp_f32_e32 v92, v92
	v_exp_f32_e32 v93, v93
	v_exp_f32_e32 v94, v94
	v_exp_f32_e32 v95, v95
	v_add_f32_e32 v88, 1.0, v88
	v_add_f32_e32 v89, 1.0, v89
	v_add_f32_e32 v90, 1.0, v90
	v_add_f32_e32 v91, 1.0, v91
	v_add_f32_e32 v92, 1.0, v92
	v_add_f32_e32 v93, 1.0, v93
	v_add_f32_e32 v94, 1.0, v94
	v_add_f32_e32 v95, 1.0, v95
	v_rcp_f32_e32 v88, v88
	v_rcp_f32_e32 v89, v89
	v_rcp_f32_e32 v90, v90
	v_rcp_f32_e32 v91, v91
	v_rcp_f32_e32 v92, v92
	v_rcp_f32_e32 v93, v93
	v_rcp_f32_e32 v94, v94
	v_rcp_f32_e32 v95, v95
	v_mul_f32_e32 v88, v84, v88
	v_mul_f32_e32 v89, v85, v89
	v_mul_f32_e32 v90, v86, v90
	v_mul_f32_e32 v91, v87, v91
	v_mul_f32_e32 v92, v80, v92
	v_mul_f32_e32 v93, v81, v93
	v_mul_f32_e32 v94, v82, v94
	v_mul_f32_e32 v95, v83, v95
	v_cvt_pk_bf16_f32 v88, v88, v89
	v_cvt_pk_bf16_f32 v89, v90, v91
	v_cvt_pk_bf16_f32 v90, v92, v93
	v_cvt_pk_bf16_f32 v91, v94, v95
	global_store_dwordx4 v174, v[88:91], s[60:61] offset:256
	s_add_u32 s60, s60, s64
	s_addc_u32 s61, s61, 0
	v_mul_f32_e32 v80, 0x3d372713, v76
	v_mul_f32_e32 v81, 0x3d372713, v77
	v_mul_f32_e32 v82, 0x3d372713, v78
	v_mul_f32_e32 v83, 0x3d372713, v79
	v_mul_f32_e32 v84, 0x3d372713, v72
	v_mul_f32_e32 v85, 0x3d372713, v73
	v_mul_f32_e32 v86, 0x3d372713, v74
	v_mul_f32_e32 v87, 0x3d372713, v75
	v_mul_f32_e32 v80, v76, v80
	v_mul_f32_e32 v81, v77, v81
	v_mul_f32_e32 v82, v78, v82
	v_mul_f32_e32 v83, v79, v83
	v_mul_f32_e32 v84, v72, v84
	v_mul_f32_e32 v85, v73, v85
	v_mul_f32_e32 v86, v74, v86
	v_mul_f32_e32 v87, v75, v87
	v_fma_f32 v80, v76, v80, v76
	v_fma_f32 v81, v77, v81, v77
	v_fma_f32 v82, v78, v82, v78
	v_fma_f32 v83, v79, v83, v79
	v_fma_f32 v84, v72, v84, v72
	v_fma_f32 v85, v73, v85, v73
	v_fma_f32 v86, v74, v86, v74
	v_fma_f32 v87, v75, v87, v75
	v_mul_f32_e32 v80, 0x3fcc422a, v80
	v_mul_f32_e32 v81, 0x3fcc422a, v81
	v_mul_f32_e32 v82, 0x3fcc422a, v82
	v_mul_f32_e32 v83, 0x3fcc422a, v83
	v_mul_f32_e32 v84, 0x3fcc422a, v84
	v_mul_f32_e32 v85, 0x3fcc422a, v85
	v_mul_f32_e32 v86, 0x3fcc422a, v86
	v_mul_f32_e32 v87, 0x3fcc422a, v87
	v_mul_f32_e32 v80, 0xbfb8aa3b, v80
	v_mul_f32_e32 v81, 0xbfb8aa3b, v81
	v_mul_f32_e32 v82, 0xbfb8aa3b, v82
	v_mul_f32_e32 v83, 0xbfb8aa3b, v83
	v_mul_f32_e32 v84, 0xbfb8aa3b, v84
	v_mul_f32_e32 v85, 0xbfb8aa3b, v85
	v_mul_f32_e32 v86, 0xbfb8aa3b, v86
	v_mul_f32_e32 v87, 0xbfb8aa3b, v87
	v_exp_f32_e32 v80, v80
	v_exp_f32_e32 v81, v81
	v_exp_f32_e32 v82, v82
	v_exp_f32_e32 v83, v83
	v_exp_f32_e32 v84, v84
	v_exp_f32_e32 v85, v85
	v_exp_f32_e32 v86, v86
	v_exp_f32_e32 v87, v87
	v_add_f32_e32 v80, 1.0, v80
	v_add_f32_e32 v81, 1.0, v81
	v_add_f32_e32 v82, 1.0, v82
	v_add_f32_e32 v83, 1.0, v83
	v_add_f32_e32 v84, 1.0, v84
	v_add_f32_e32 v85, 1.0, v85
	v_add_f32_e32 v86, 1.0, v86
	v_add_f32_e32 v87, 1.0, v87
	v_rcp_f32_e32 v80, v80
	v_rcp_f32_e32 v81, v81
	v_rcp_f32_e32 v82, v82
	v_rcp_f32_e32 v83, v83
	v_rcp_f32_e32 v84, v84
	v_rcp_f32_e32 v85, v85
	v_rcp_f32_e32 v86, v86
	v_rcp_f32_e32 v87, v87
	v_mul_f32_e32 v80, v76, v80
	v_mul_f32_e32 v81, v77, v81
	v_mul_f32_e32 v82, v78, v82
	v_mul_f32_e32 v83, v79, v83
	v_mul_f32_e32 v84, v72, v84
	v_mul_f32_e32 v85, v73, v85
	v_mul_f32_e32 v86, v74, v86
	v_mul_f32_e32 v87, v75, v87
	v_cvt_pk_bf16_f32 v80, v80, v81
	v_cvt_pk_bf16_f32 v81, v82, v83
	v_cvt_pk_bf16_f32 v82, v84, v85
	v_cvt_pk_bf16_f32 v83, v86, v87
	global_store_dwordx4 v174, v[80:83], s[60:61]
	v_mul_f32_e32 v72, 0x3d372713, v68
	v_mul_f32_e32 v73, 0x3d372713, v69
	v_mul_f32_e32 v74, 0x3d372713, v70
	v_mul_f32_e32 v75, 0x3d372713, v71
	v_mul_f32_e32 v76, 0x3d372713, v64
	v_mul_f32_e32 v77, 0x3d372713, v65
	v_mul_f32_e32 v78, 0x3d372713, v66
	v_mul_f32_e32 v79, 0x3d372713, v67
	v_mul_f32_e32 v72, v68, v72
	v_mul_f32_e32 v73, v69, v73
	v_mul_f32_e32 v74, v70, v74
	v_mul_f32_e32 v75, v71, v75
	v_mul_f32_e32 v76, v64, v76
	v_mul_f32_e32 v77, v65, v77
	v_mul_f32_e32 v78, v66, v78
	v_mul_f32_e32 v79, v67, v79
	v_fma_f32 v72, v68, v72, v68
	v_fma_f32 v73, v69, v73, v69
	v_fma_f32 v74, v70, v74, v70
	v_fma_f32 v75, v71, v75, v71
	v_fma_f32 v76, v64, v76, v64
	v_fma_f32 v77, v65, v77, v65
	v_fma_f32 v78, v66, v78, v66
	v_fma_f32 v79, v67, v79, v67
	v_mul_f32_e32 v72, 0x3fcc422a, v72
	v_mul_f32_e32 v73, 0x3fcc422a, v73
	v_mul_f32_e32 v74, 0x3fcc422a, v74
	v_mul_f32_e32 v75, 0x3fcc422a, v75
	v_mul_f32_e32 v76, 0x3fcc422a, v76
	v_mul_f32_e32 v77, 0x3fcc422a, v77
	v_mul_f32_e32 v78, 0x3fcc422a, v78
	v_mul_f32_e32 v79, 0x3fcc422a, v79
	v_mul_f32_e32 v72, 0xbfb8aa3b, v72
	v_mul_f32_e32 v73, 0xbfb8aa3b, v73
	v_mul_f32_e32 v74, 0xbfb8aa3b, v74
	v_mul_f32_e32 v75, 0xbfb8aa3b, v75
	v_mul_f32_e32 v76, 0xbfb8aa3b, v76
	v_mul_f32_e32 v77, 0xbfb8aa3b, v77
	v_mul_f32_e32 v78, 0xbfb8aa3b, v78
	v_mul_f32_e32 v79, 0xbfb8aa3b, v79
	v_exp_f32_e32 v72, v72
	v_exp_f32_e32 v73, v73
	v_exp_f32_e32 v74, v74
	v_exp_f32_e32 v75, v75
	v_exp_f32_e32 v76, v76
	v_exp_f32_e32 v77, v77
	v_exp_f32_e32 v78, v78
	v_exp_f32_e32 v79, v79
	v_add_f32_e32 v72, 1.0, v72
	v_add_f32_e32 v73, 1.0, v73
	v_add_f32_e32 v74, 1.0, v74
	v_add_f32_e32 v75, 1.0, v75
	v_add_f32_e32 v76, 1.0, v76
	v_add_f32_e32 v77, 1.0, v77
	v_add_f32_e32 v78, 1.0, v78
	v_add_f32_e32 v79, 1.0, v79
	v_rcp_f32_e32 v72, v72
	v_rcp_f32_e32 v73, v73
	v_rcp_f32_e32 v74, v74
	v_rcp_f32_e32 v75, v75
	v_rcp_f32_e32 v76, v76
	v_rcp_f32_e32 v77, v77
	v_rcp_f32_e32 v78, v78
	v_rcp_f32_e32 v79, v79
	v_mul_f32_e32 v72, v68, v72
	v_mul_f32_e32 v73, v69, v73
	v_mul_f32_e32 v74, v70, v74
	v_mul_f32_e32 v75, v71, v75
	v_mul_f32_e32 v76, v64, v76
	v_mul_f32_e32 v77, v65, v77
	v_mul_f32_e32 v78, v66, v78
	v_mul_f32_e32 v79, v67, v79
	v_cvt_pk_bf16_f32 v72, v72, v73
	v_cvt_pk_bf16_f32 v73, v74, v75
	v_cvt_pk_bf16_f32 v74, v76, v77
	v_cvt_pk_bf16_f32 v75, v78, v79
	global_store_dwordx4 v174, v[72:75], s[60:61] offset:256
	s_add_u32 s60, s60, s64
	s_addc_u32 s61, s61, 0
	s_add_u32 s60, s60, s65
	s_addc_u32 s61, s61, 0
	v_mul_f32_e32 v64, 0x3d372713, v60
	v_mul_f32_e32 v65, 0x3d372713, v61
	v_mul_f32_e32 v66, 0x3d372713, v62
	v_mul_f32_e32 v67, 0x3d372713, v63
	v_mul_f32_e32 v68, 0x3d372713, v56
	v_mul_f32_e32 v69, 0x3d372713, v57
	v_mul_f32_e32 v70, 0x3d372713, v58
	v_mul_f32_e32 v71, 0x3d372713, v59
	v_mul_f32_e32 v64, v60, v64
	v_mul_f32_e32 v65, v61, v65
	v_mul_f32_e32 v66, v62, v66
	v_mul_f32_e32 v67, v63, v67
	v_mul_f32_e32 v68, v56, v68
	v_mul_f32_e32 v69, v57, v69
	v_mul_f32_e32 v70, v58, v70
	v_mul_f32_e32 v71, v59, v71
	v_fma_f32 v64, v60, v64, v60
	v_fma_f32 v65, v61, v65, v61
	v_fma_f32 v66, v62, v66, v62
	v_fma_f32 v67, v63, v67, v63
	v_fma_f32 v68, v56, v68, v56
	v_fma_f32 v69, v57, v69, v57
	v_fma_f32 v70, v58, v70, v58
	v_fma_f32 v71, v59, v71, v59
	v_mul_f32_e32 v64, 0x3fcc422a, v64
	v_mul_f32_e32 v65, 0x3fcc422a, v65
	v_mul_f32_e32 v66, 0x3fcc422a, v66
	v_mul_f32_e32 v67, 0x3fcc422a, v67
	v_mul_f32_e32 v68, 0x3fcc422a, v68
	v_mul_f32_e32 v69, 0x3fcc422a, v69
	v_mul_f32_e32 v70, 0x3fcc422a, v70
	v_mul_f32_e32 v71, 0x3fcc422a, v71
	v_mul_f32_e32 v64, 0xbfb8aa3b, v64
	v_mul_f32_e32 v65, 0xbfb8aa3b, v65
	v_mul_f32_e32 v66, 0xbfb8aa3b, v66
	v_mul_f32_e32 v67, 0xbfb8aa3b, v67
	v_mul_f32_e32 v68, 0xbfb8aa3b, v68
	v_mul_f32_e32 v69, 0xbfb8aa3b, v69
	v_mul_f32_e32 v70, 0xbfb8aa3b, v70
	v_mul_f32_e32 v71, 0xbfb8aa3b, v71
	v_exp_f32_e32 v64, v64
	v_exp_f32_e32 v65, v65
	v_exp_f32_e32 v66, v66
	v_exp_f32_e32 v67, v67
	v_exp_f32_e32 v68, v68
	v_exp_f32_e32 v69, v69
	v_exp_f32_e32 v70, v70
	v_exp_f32_e32 v71, v71
	v_add_f32_e32 v64, 1.0, v64
	v_add_f32_e32 v65, 1.0, v65
	v_add_f32_e32 v66, 1.0, v66
	v_add_f32_e32 v67, 1.0, v67
	v_add_f32_e32 v68, 1.0, v68
	v_add_f32_e32 v69, 1.0, v69
	v_add_f32_e32 v70, 1.0, v70
	v_add_f32_e32 v71, 1.0, v71
	v_rcp_f32_e32 v64, v64
	v_rcp_f32_e32 v65, v65
	v_rcp_f32_e32 v66, v66
	v_rcp_f32_e32 v67, v67
	v_rcp_f32_e32 v68, v68
	v_rcp_f32_e32 v69, v69
	v_rcp_f32_e32 v70, v70
	v_rcp_f32_e32 v71, v71
	v_mul_f32_e32 v64, v60, v64
	v_mul_f32_e32 v65, v61, v65
	v_mul_f32_e32 v66, v62, v66
	v_mul_f32_e32 v67, v63, v67
	v_mul_f32_e32 v68, v56, v68
	v_mul_f32_e32 v69, v57, v69
	v_mul_f32_e32 v70, v58, v70
	v_mul_f32_e32 v71, v59, v71
	v_cvt_pk_bf16_f32 v64, v64, v65
	v_cvt_pk_bf16_f32 v65, v66, v67
	v_cvt_pk_bf16_f32 v66, v68, v69
	v_cvt_pk_bf16_f32 v67, v70, v71
	global_store_dwordx4 v174, v[64:67], s[60:61]
	v_mul_f32_e32 v56, 0x3d372713, v52
	v_mul_f32_e32 v57, 0x3d372713, v53
	v_mul_f32_e32 v58, 0x3d372713, v54
	v_mul_f32_e32 v59, 0x3d372713, v55
	v_mul_f32_e32 v60, 0x3d372713, v48
	v_mul_f32_e32 v61, 0x3d372713, v49
	v_mul_f32_e32 v62, 0x3d372713, v50
	v_mul_f32_e32 v63, 0x3d372713, v51
	v_mul_f32_e32 v56, v52, v56
	v_mul_f32_e32 v57, v53, v57
	v_mul_f32_e32 v58, v54, v58
	v_mul_f32_e32 v59, v55, v59
	v_mul_f32_e32 v60, v48, v60
	v_mul_f32_e32 v61, v49, v61
	v_mul_f32_e32 v62, v50, v62
	v_mul_f32_e32 v63, v51, v63
	v_fma_f32 v56, v52, v56, v52
	v_fma_f32 v57, v53, v57, v53
	v_fma_f32 v58, v54, v58, v54
	v_fma_f32 v59, v55, v59, v55
	v_fma_f32 v60, v48, v60, v48
	v_fma_f32 v61, v49, v61, v49
	v_fma_f32 v62, v50, v62, v50
	v_fma_f32 v63, v51, v63, v51
	v_mul_f32_e32 v56, 0x3fcc422a, v56
	v_mul_f32_e32 v57, 0x3fcc422a, v57
	v_mul_f32_e32 v58, 0x3fcc422a, v58
	v_mul_f32_e32 v59, 0x3fcc422a, v59
	v_mul_f32_e32 v60, 0x3fcc422a, v60
	v_mul_f32_e32 v61, 0x3fcc422a, v61
	v_mul_f32_e32 v62, 0x3fcc422a, v62
	v_mul_f32_e32 v63, 0x3fcc422a, v63
	v_mul_f32_e32 v56, 0xbfb8aa3b, v56
	v_mul_f32_e32 v57, 0xbfb8aa3b, v57
	v_mul_f32_e32 v58, 0xbfb8aa3b, v58
	v_mul_f32_e32 v59, 0xbfb8aa3b, v59
	v_mul_f32_e32 v60, 0xbfb8aa3b, v60
	v_mul_f32_e32 v61, 0xbfb8aa3b, v61
	v_mul_f32_e32 v62, 0xbfb8aa3b, v62
	v_mul_f32_e32 v63, 0xbfb8aa3b, v63
	v_exp_f32_e32 v56, v56
	v_exp_f32_e32 v57, v57
	v_exp_f32_e32 v58, v58
	v_exp_f32_e32 v59, v59
	v_exp_f32_e32 v60, v60
	v_exp_f32_e32 v61, v61
	v_exp_f32_e32 v62, v62
	v_exp_f32_e32 v63, v63
	v_add_f32_e32 v56, 1.0, v56
	v_add_f32_e32 v57, 1.0, v57
	v_add_f32_e32 v58, 1.0, v58
	v_add_f32_e32 v59, 1.0, v59
	v_add_f32_e32 v60, 1.0, v60
	v_add_f32_e32 v61, 1.0, v61
	v_add_f32_e32 v62, 1.0, v62
	v_add_f32_e32 v63, 1.0, v63
	v_rcp_f32_e32 v56, v56
	v_rcp_f32_e32 v57, v57
	v_rcp_f32_e32 v58, v58
	v_rcp_f32_e32 v59, v59
	v_rcp_f32_e32 v60, v60
	v_rcp_f32_e32 v61, v61
	v_rcp_f32_e32 v62, v62
	v_rcp_f32_e32 v63, v63
	v_mul_f32_e32 v56, v52, v56
	v_mul_f32_e32 v57, v53, v57
	v_mul_f32_e32 v58, v54, v58
	v_mul_f32_e32 v59, v55, v59
	v_mul_f32_e32 v60, v48, v60
	v_mul_f32_e32 v61, v49, v61
	v_mul_f32_e32 v62, v50, v62
	v_mul_f32_e32 v63, v51, v63
	v_cvt_pk_bf16_f32 v56, v56, v57
	v_cvt_pk_bf16_f32 v57, v58, v59
	v_cvt_pk_bf16_f32 v58, v60, v61
	v_cvt_pk_bf16_f32 v59, v62, v63
	global_store_dwordx4 v174, v[56:59], s[60:61] offset:256
	s_add_u32 s60, s60, s64
	s_addc_u32 s61, s61, 0
	v_mul_f32_e32 v48, 0x3d372713, v44
	v_mul_f32_e32 v49, 0x3d372713, v45
	v_mul_f32_e32 v50, 0x3d372713, v46
	v_mul_f32_e32 v51, 0x3d372713, v47
	v_mul_f32_e32 v52, 0x3d372713, v40
	v_mul_f32_e32 v53, 0x3d372713, v41
	v_mul_f32_e32 v54, 0x3d372713, v42
	v_mul_f32_e32 v55, 0x3d372713, v43
	v_mul_f32_e32 v48, v44, v48
	v_mul_f32_e32 v49, v45, v49
	v_mul_f32_e32 v50, v46, v50
	v_mul_f32_e32 v51, v47, v51
	v_mul_f32_e32 v52, v40, v52
	v_mul_f32_e32 v53, v41, v53
	v_mul_f32_e32 v54, v42, v54
	v_mul_f32_e32 v55, v43, v55
	v_fma_f32 v48, v44, v48, v44
	v_fma_f32 v49, v45, v49, v45
	v_fma_f32 v50, v46, v50, v46
	v_fma_f32 v51, v47, v51, v47
	v_fma_f32 v52, v40, v52, v40
	v_fma_f32 v53, v41, v53, v41
	v_fma_f32 v54, v42, v54, v42
	v_fma_f32 v55, v43, v55, v43
	v_mul_f32_e32 v48, 0x3fcc422a, v48
	v_mul_f32_e32 v49, 0x3fcc422a, v49
	v_mul_f32_e32 v50, 0x3fcc422a, v50
	v_mul_f32_e32 v51, 0x3fcc422a, v51
	v_mul_f32_e32 v52, 0x3fcc422a, v52
	v_mul_f32_e32 v53, 0x3fcc422a, v53
	v_mul_f32_e32 v54, 0x3fcc422a, v54
	v_mul_f32_e32 v55, 0x3fcc422a, v55
	v_mul_f32_e32 v48, 0xbfb8aa3b, v48
	v_mul_f32_e32 v49, 0xbfb8aa3b, v49
	v_mul_f32_e32 v50, 0xbfb8aa3b, v50
	v_mul_f32_e32 v51, 0xbfb8aa3b, v51
	v_mul_f32_e32 v52, 0xbfb8aa3b, v52
	v_mul_f32_e32 v53, 0xbfb8aa3b, v53
	v_mul_f32_e32 v54, 0xbfb8aa3b, v54
	v_mul_f32_e32 v55, 0xbfb8aa3b, v55
	v_exp_f32_e32 v48, v48
	v_exp_f32_e32 v49, v49
	v_exp_f32_e32 v50, v50
	v_exp_f32_e32 v51, v51
	v_exp_f32_e32 v52, v52
	v_exp_f32_e32 v53, v53
	v_exp_f32_e32 v54, v54
	v_exp_f32_e32 v55, v55
	v_add_f32_e32 v48, 1.0, v48
	v_add_f32_e32 v49, 1.0, v49
	v_add_f32_e32 v50, 1.0, v50
	v_add_f32_e32 v51, 1.0, v51
	v_add_f32_e32 v52, 1.0, v52
	v_add_f32_e32 v53, 1.0, v53
	v_add_f32_e32 v54, 1.0, v54
	v_add_f32_e32 v55, 1.0, v55
	v_rcp_f32_e32 v48, v48
	v_rcp_f32_e32 v49, v49
	v_rcp_f32_e32 v50, v50
	v_rcp_f32_e32 v51, v51
	v_rcp_f32_e32 v52, v52
	v_rcp_f32_e32 v53, v53
	v_rcp_f32_e32 v54, v54
	v_rcp_f32_e32 v55, v55
	v_mul_f32_e32 v48, v44, v48
	v_mul_f32_e32 v49, v45, v49
	v_mul_f32_e32 v50, v46, v50
	v_mul_f32_e32 v51, v47, v51
	v_mul_f32_e32 v52, v40, v52
	v_mul_f32_e32 v53, v41, v53
	v_mul_f32_e32 v54, v42, v54
	v_mul_f32_e32 v55, v43, v55
	v_cvt_pk_bf16_f32 v48, v48, v49
	v_cvt_pk_bf16_f32 v49, v50, v51
	v_cvt_pk_bf16_f32 v50, v52, v53
	v_cvt_pk_bf16_f32 v51, v54, v55
	global_store_dwordx4 v174, v[48:51], s[60:61]
	v_mul_f32_e32 v40, 0x3d372713, v36
	v_mul_f32_e32 v41, 0x3d372713, v37
	v_mul_f32_e32 v42, 0x3d372713, v38
	v_mul_f32_e32 v43, 0x3d372713, v39
	v_mul_f32_e32 v44, 0x3d372713, v32
	v_mul_f32_e32 v45, 0x3d372713, v33
	v_mul_f32_e32 v46, 0x3d372713, v34
	v_mul_f32_e32 v47, 0x3d372713, v35
	v_mul_f32_e32 v40, v36, v40
	v_mul_f32_e32 v41, v37, v41
	v_mul_f32_e32 v42, v38, v42
	v_mul_f32_e32 v43, v39, v43
	v_mul_f32_e32 v44, v32, v44
	v_mul_f32_e32 v45, v33, v45
	v_mul_f32_e32 v46, v34, v46
	v_mul_f32_e32 v47, v35, v47
	v_fma_f32 v40, v36, v40, v36
	v_fma_f32 v41, v37, v41, v37
	v_fma_f32 v42, v38, v42, v38
	v_fma_f32 v43, v39, v43, v39
	v_fma_f32 v44, v32, v44, v32
	v_fma_f32 v45, v33, v45, v33
	v_fma_f32 v46, v34, v46, v34
	v_fma_f32 v47, v35, v47, v35
	v_mul_f32_e32 v40, 0x3fcc422a, v40
	v_mul_f32_e32 v41, 0x3fcc422a, v41
	v_mul_f32_e32 v42, 0x3fcc422a, v42
	v_mul_f32_e32 v43, 0x3fcc422a, v43
	v_mul_f32_e32 v44, 0x3fcc422a, v44
	v_mul_f32_e32 v45, 0x3fcc422a, v45
	v_mul_f32_e32 v46, 0x3fcc422a, v46
	v_mul_f32_e32 v47, 0x3fcc422a, v47
	v_mul_f32_e32 v40, 0xbfb8aa3b, v40
	v_mul_f32_e32 v41, 0xbfb8aa3b, v41
	v_mul_f32_e32 v42, 0xbfb8aa3b, v42
	v_mul_f32_e32 v43, 0xbfb8aa3b, v43
	v_mul_f32_e32 v44, 0xbfb8aa3b, v44
	v_mul_f32_e32 v45, 0xbfb8aa3b, v45
	v_mul_f32_e32 v46, 0xbfb8aa3b, v46
	v_mul_f32_e32 v47, 0xbfb8aa3b, v47
	v_exp_f32_e32 v40, v40
	v_exp_f32_e32 v41, v41
	v_exp_f32_e32 v42, v42
	v_exp_f32_e32 v43, v43
	v_exp_f32_e32 v44, v44
	v_exp_f32_e32 v45, v45
	v_exp_f32_e32 v46, v46
	v_exp_f32_e32 v47, v47
	v_add_f32_e32 v40, 1.0, v40
	v_add_f32_e32 v41, 1.0, v41
	v_add_f32_e32 v42, 1.0, v42
	v_add_f32_e32 v43, 1.0, v43
	v_add_f32_e32 v44, 1.0, v44
	v_add_f32_e32 v45, 1.0, v45
	v_add_f32_e32 v46, 1.0, v46
	v_add_f32_e32 v47, 1.0, v47
	v_rcp_f32_e32 v40, v40
	v_rcp_f32_e32 v41, v41
	v_rcp_f32_e32 v42, v42
	v_rcp_f32_e32 v43, v43
	v_rcp_f32_e32 v44, v44
	v_rcp_f32_e32 v45, v45
	v_rcp_f32_e32 v46, v46
	v_rcp_f32_e32 v47, v47
	v_mul_f32_e32 v40, v36, v40
	v_mul_f32_e32 v41, v37, v41
	v_mul_f32_e32 v42, v38, v42
	v_mul_f32_e32 v43, v39, v43
	v_mul_f32_e32 v44, v32, v44
	v_mul_f32_e32 v45, v33, v45
	v_mul_f32_e32 v46, v34, v46
	v_mul_f32_e32 v47, v35, v47
	v_cvt_pk_bf16_f32 v40, v40, v41
	v_cvt_pk_bf16_f32 v41, v42, v43
	v_cvt_pk_bf16_f32 v42, v44, v45
	v_cvt_pk_bf16_f32 v43, v46, v47
	global_store_dwordx4 v174, v[40:43], s[60:61] offset:256
	s_add_u32 s60, s60, s64
	s_addc_u32 s61, s61, 0
	v_mul_f32_e32 v32, 0x3d372713, v28
	v_mul_f32_e32 v33, 0x3d372713, v29
	v_mul_f32_e32 v34, 0x3d372713, v30
	v_mul_f32_e32 v35, 0x3d372713, v31
	v_mul_f32_e32 v36, 0x3d372713, v24
	v_mul_f32_e32 v37, 0x3d372713, v25
	v_mul_f32_e32 v38, 0x3d372713, v26
	v_mul_f32_e32 v39, 0x3d372713, v27
	v_mul_f32_e32 v32, v28, v32
	v_mul_f32_e32 v33, v29, v33
	v_mul_f32_e32 v34, v30, v34
	v_mul_f32_e32 v35, v31, v35
	v_mul_f32_e32 v36, v24, v36
	v_mul_f32_e32 v37, v25, v37
	v_mul_f32_e32 v38, v26, v38
	v_mul_f32_e32 v39, v27, v39
	v_fma_f32 v32, v28, v32, v28
	v_fma_f32 v33, v29, v33, v29
	v_fma_f32 v34, v30, v34, v30
	v_fma_f32 v35, v31, v35, v31
	v_fma_f32 v36, v24, v36, v24
	v_fma_f32 v37, v25, v37, v25
	v_fma_f32 v38, v26, v38, v26
	v_fma_f32 v39, v27, v39, v27
	v_mul_f32_e32 v32, 0x3fcc422a, v32
	v_mul_f32_e32 v33, 0x3fcc422a, v33
	v_mul_f32_e32 v34, 0x3fcc422a, v34
	v_mul_f32_e32 v35, 0x3fcc422a, v35
	v_mul_f32_e32 v36, 0x3fcc422a, v36
	v_mul_f32_e32 v37, 0x3fcc422a, v37
	v_mul_f32_e32 v38, 0x3fcc422a, v38
	v_mul_f32_e32 v39, 0x3fcc422a, v39
	v_mul_f32_e32 v32, 0xbfb8aa3b, v32
	v_mul_f32_e32 v33, 0xbfb8aa3b, v33
	v_mul_f32_e32 v34, 0xbfb8aa3b, v34
	v_mul_f32_e32 v35, 0xbfb8aa3b, v35
	v_mul_f32_e32 v36, 0xbfb8aa3b, v36
	v_mul_f32_e32 v37, 0xbfb8aa3b, v37
	v_mul_f32_e32 v38, 0xbfb8aa3b, v38
	v_mul_f32_e32 v39, 0xbfb8aa3b, v39
	v_exp_f32_e32 v32, v32
	v_exp_f32_e32 v33, v33
	v_exp_f32_e32 v34, v34
	v_exp_f32_e32 v35, v35
	v_exp_f32_e32 v36, v36
	v_exp_f32_e32 v37, v37
	v_exp_f32_e32 v38, v38
	v_exp_f32_e32 v39, v39
	v_add_f32_e32 v32, 1.0, v32
	v_add_f32_e32 v33, 1.0, v33
	v_add_f32_e32 v34, 1.0, v34
	v_add_f32_e32 v35, 1.0, v35
	v_add_f32_e32 v36, 1.0, v36
	v_add_f32_e32 v37, 1.0, v37
	v_add_f32_e32 v38, 1.0, v38
	v_add_f32_e32 v39, 1.0, v39
	v_rcp_f32_e32 v32, v32
	v_rcp_f32_e32 v33, v33
	v_rcp_f32_e32 v34, v34
	v_rcp_f32_e32 v35, v35
	v_rcp_f32_e32 v36, v36
	v_rcp_f32_e32 v37, v37
	v_rcp_f32_e32 v38, v38
	v_rcp_f32_e32 v39, v39
	v_mul_f32_e32 v32, v28, v32
	v_mul_f32_e32 v33, v29, v33
	v_mul_f32_e32 v34, v30, v34
	v_mul_f32_e32 v35, v31, v35
	v_mul_f32_e32 v36, v24, v36
	v_mul_f32_e32 v37, v25, v37
	v_mul_f32_e32 v38, v26, v38
	v_mul_f32_e32 v39, v27, v39
	v_cvt_pk_bf16_f32 v32, v32, v33
	v_cvt_pk_bf16_f32 v33, v34, v35
	v_cvt_pk_bf16_f32 v34, v36, v37
	v_cvt_pk_bf16_f32 v35, v38, v39
	global_store_dwordx4 v174, v[32:35], s[60:61]
	v_mul_f32_e32 v24, 0x3d372713, v20
	v_mul_f32_e32 v25, 0x3d372713, v21
	v_mul_f32_e32 v26, 0x3d372713, v22
	v_mul_f32_e32 v27, 0x3d372713, v23
	v_mul_f32_e32 v28, 0x3d372713, v16
	v_mul_f32_e32 v29, 0x3d372713, v17
	v_mul_f32_e32 v30, 0x3d372713, v18
	v_mul_f32_e32 v31, 0x3d372713, v19
	v_mul_f32_e32 v24, v20, v24
	v_mul_f32_e32 v25, v21, v25
	v_mul_f32_e32 v26, v22, v26
	v_mul_f32_e32 v27, v23, v27
	v_mul_f32_e32 v28, v16, v28
	v_mul_f32_e32 v29, v17, v29
	v_mul_f32_e32 v30, v18, v30
	v_mul_f32_e32 v31, v19, v31
	v_fma_f32 v24, v20, v24, v20
	v_fma_f32 v25, v21, v25, v21
	v_fma_f32 v26, v22, v26, v22
	v_fma_f32 v27, v23, v27, v23
	v_fma_f32 v28, v16, v28, v16
	v_fma_f32 v29, v17, v29, v17
	v_fma_f32 v30, v18, v30, v18
	v_fma_f32 v31, v19, v31, v19
	v_mul_f32_e32 v24, 0x3fcc422a, v24
	v_mul_f32_e32 v25, 0x3fcc422a, v25
	v_mul_f32_e32 v26, 0x3fcc422a, v26
	v_mul_f32_e32 v27, 0x3fcc422a, v27
	v_mul_f32_e32 v28, 0x3fcc422a, v28
	v_mul_f32_e32 v29, 0x3fcc422a, v29
	v_mul_f32_e32 v30, 0x3fcc422a, v30
	v_mul_f32_e32 v31, 0x3fcc422a, v31
	v_mul_f32_e32 v24, 0xbfb8aa3b, v24
	v_mul_f32_e32 v25, 0xbfb8aa3b, v25
	v_mul_f32_e32 v26, 0xbfb8aa3b, v26
	v_mul_f32_e32 v27, 0xbfb8aa3b, v27
	v_mul_f32_e32 v28, 0xbfb8aa3b, v28
	v_mul_f32_e32 v29, 0xbfb8aa3b, v29
	v_mul_f32_e32 v30, 0xbfb8aa3b, v30
	v_mul_f32_e32 v31, 0xbfb8aa3b, v31
	v_exp_f32_e32 v24, v24
	v_exp_f32_e32 v25, v25
	v_exp_f32_e32 v26, v26
	v_exp_f32_e32 v27, v27
	v_exp_f32_e32 v28, v28
	v_exp_f32_e32 v29, v29
	v_exp_f32_e32 v30, v30
	v_exp_f32_e32 v31, v31
	v_add_f32_e32 v24, 1.0, v24
	v_add_f32_e32 v25, 1.0, v25
	v_add_f32_e32 v26, 1.0, v26
	v_add_f32_e32 v27, 1.0, v27
	v_add_f32_e32 v28, 1.0, v28
	v_add_f32_e32 v29, 1.0, v29
	v_add_f32_e32 v30, 1.0, v30
	v_add_f32_e32 v31, 1.0, v31
	v_rcp_f32_e32 v24, v24
	v_rcp_f32_e32 v25, v25
	v_rcp_f32_e32 v26, v26
	v_rcp_f32_e32 v27, v27
	v_rcp_f32_e32 v28, v28
	v_rcp_f32_e32 v29, v29
	v_rcp_f32_e32 v30, v30
	v_rcp_f32_e32 v31, v31
	v_mul_f32_e32 v24, v20, v24
	v_mul_f32_e32 v25, v21, v25
	v_mul_f32_e32 v26, v22, v26
	v_mul_f32_e32 v27, v23, v27
	v_mul_f32_e32 v28, v16, v28
	v_mul_f32_e32 v29, v17, v29
	v_mul_f32_e32 v30, v18, v30
	v_mul_f32_e32 v31, v19, v31
	v_cvt_pk_bf16_f32 v24, v24, v25
	v_cvt_pk_bf16_f32 v25, v26, v27
	v_cvt_pk_bf16_f32 v26, v28, v29
	v_cvt_pk_bf16_f32 v27, v30, v31
	global_store_dwordx4 v174, v[24:27], s[60:61] offset:256
	s_add_u32 s60, s60, s64
	s_addc_u32 s61, s61, 0
	v_mul_f32_e32 v16, 0x3d372713, v12
	v_mul_f32_e32 v17, 0x3d372713, v13
	v_mul_f32_e32 v18, 0x3d372713, v14
	v_mul_f32_e32 v19, 0x3d372713, v15
	v_mul_f32_e32 v20, 0x3d372713, v8
	v_mul_f32_e32 v21, 0x3d372713, v9
	v_mul_f32_e32 v22, 0x3d372713, v10
	v_mul_f32_e32 v23, 0x3d372713, v11
	v_mul_f32_e32 v16, v12, v16
	v_mul_f32_e32 v17, v13, v17
	v_mul_f32_e32 v18, v14, v18
	v_mul_f32_e32 v19, v15, v19
	v_mul_f32_e32 v20, v8, v20
	v_mul_f32_e32 v21, v9, v21
	v_mul_f32_e32 v22, v10, v22
	v_mul_f32_e32 v23, v11, v23
	v_fma_f32 v16, v12, v16, v12
	v_fma_f32 v17, v13, v17, v13
	v_fma_f32 v18, v14, v18, v14
	v_fma_f32 v19, v15, v19, v15
	v_fma_f32 v20, v8, v20, v8
	v_fma_f32 v21, v9, v21, v9
	v_fma_f32 v22, v10, v22, v10
	v_fma_f32 v23, v11, v23, v11
	v_mul_f32_e32 v16, 0x3fcc422a, v16
	v_mul_f32_e32 v17, 0x3fcc422a, v17
	v_mul_f32_e32 v18, 0x3fcc422a, v18
	v_mul_f32_e32 v19, 0x3fcc422a, v19
	v_mul_f32_e32 v20, 0x3fcc422a, v20
	v_mul_f32_e32 v21, 0x3fcc422a, v21
	v_mul_f32_e32 v22, 0x3fcc422a, v22
	v_mul_f32_e32 v23, 0x3fcc422a, v23
	v_mul_f32_e32 v16, 0xbfb8aa3b, v16
	v_mul_f32_e32 v17, 0xbfb8aa3b, v17
	v_mul_f32_e32 v18, 0xbfb8aa3b, v18
	v_mul_f32_e32 v19, 0xbfb8aa3b, v19
	v_mul_f32_e32 v20, 0xbfb8aa3b, v20
	v_mul_f32_e32 v21, 0xbfb8aa3b, v21
	v_mul_f32_e32 v22, 0xbfb8aa3b, v22
	v_mul_f32_e32 v23, 0xbfb8aa3b, v23
	v_exp_f32_e32 v16, v16
	v_exp_f32_e32 v17, v17
	v_exp_f32_e32 v18, v18
	v_exp_f32_e32 v19, v19
	v_exp_f32_e32 v20, v20
	v_exp_f32_e32 v21, v21
	v_exp_f32_e32 v22, v22
	v_exp_f32_e32 v23, v23
	v_add_f32_e32 v16, 1.0, v16
	v_add_f32_e32 v17, 1.0, v17
	v_add_f32_e32 v18, 1.0, v18
	v_add_f32_e32 v19, 1.0, v19
	v_add_f32_e32 v20, 1.0, v20
	v_add_f32_e32 v21, 1.0, v21
	v_add_f32_e32 v22, 1.0, v22
	v_add_f32_e32 v23, 1.0, v23
	v_rcp_f32_e32 v16, v16
	v_rcp_f32_e32 v17, v17
	v_rcp_f32_e32 v18, v18
	v_rcp_f32_e32 v19, v19
	v_rcp_f32_e32 v20, v20
	v_rcp_f32_e32 v21, v21
	v_rcp_f32_e32 v22, v22
	v_rcp_f32_e32 v23, v23
	v_mul_f32_e32 v16, v12, v16
	v_mul_f32_e32 v17, v13, v17
	v_mul_f32_e32 v18, v14, v18
	v_mul_f32_e32 v19, v15, v19
	v_mul_f32_e32 v20, v8, v20
	v_mul_f32_e32 v21, v9, v21
	v_mul_f32_e32 v22, v10, v22
	v_mul_f32_e32 v23, v11, v23
	v_cvt_pk_bf16_f32 v16, v16, v17
	v_cvt_pk_bf16_f32 v17, v18, v19
	v_cvt_pk_bf16_f32 v18, v20, v21
	v_cvt_pk_bf16_f32 v19, v22, v23
	global_store_dwordx4 v174, v[16:19], s[60:61]
	v_mul_f32_e32 v8, 0x3d372713, v4
	v_mul_f32_e32 v9, 0x3d372713, v5
	v_mul_f32_e32 v10, 0x3d372713, v6
	v_mul_f32_e32 v11, 0x3d372713, v7
	v_mul_f32_e32 v12, 0x3d372713, v0
	v_mul_f32_e32 v13, 0x3d372713, v1
	v_mul_f32_e32 v14, 0x3d372713, v2
	v_mul_f32_e32 v15, 0x3d372713, v3
	v_mul_f32_e32 v8, v4, v8
	v_mul_f32_e32 v9, v5, v9
	v_mul_f32_e32 v10, v6, v10
	v_mul_f32_e32 v11, v7, v11
	v_mul_f32_e32 v12, v0, v12
	v_mul_f32_e32 v13, v1, v13
	v_mul_f32_e32 v14, v2, v14
	v_mul_f32_e32 v15, v3, v15
	v_fma_f32 v8, v4, v8, v4
	v_fma_f32 v9, v5, v9, v5
	v_fma_f32 v10, v6, v10, v6
	v_fma_f32 v11, v7, v11, v7
	v_fma_f32 v12, v0, v12, v0
	v_fma_f32 v13, v1, v13, v1
	v_fma_f32 v14, v2, v14, v2
	v_fma_f32 v15, v3, v15, v3
	v_mul_f32_e32 v8, 0x3fcc422a, v8
	v_mul_f32_e32 v9, 0x3fcc422a, v9
	v_mul_f32_e32 v10, 0x3fcc422a, v10
	v_mul_f32_e32 v11, 0x3fcc422a, v11
	v_mul_f32_e32 v12, 0x3fcc422a, v12
	v_mul_f32_e32 v13, 0x3fcc422a, v13
	v_mul_f32_e32 v14, 0x3fcc422a, v14
	v_mul_f32_e32 v15, 0x3fcc422a, v15
	v_mul_f32_e32 v8, 0xbfb8aa3b, v8
	v_mul_f32_e32 v9, 0xbfb8aa3b, v9
	v_mul_f32_e32 v10, 0xbfb8aa3b, v10
	v_mul_f32_e32 v11, 0xbfb8aa3b, v11
	v_mul_f32_e32 v12, 0xbfb8aa3b, v12
	v_mul_f32_e32 v13, 0xbfb8aa3b, v13
	v_mul_f32_e32 v14, 0xbfb8aa3b, v14
	v_mul_f32_e32 v15, 0xbfb8aa3b, v15
	v_exp_f32_e32 v8, v8
	v_exp_f32_e32 v9, v9
	v_exp_f32_e32 v10, v10
	v_exp_f32_e32 v11, v11
	v_exp_f32_e32 v12, v12
	v_exp_f32_e32 v13, v13
	v_exp_f32_e32 v14, v14
	v_exp_f32_e32 v15, v15
	v_add_f32_e32 v8, 1.0, v8
	v_add_f32_e32 v9, 1.0, v9
	v_add_f32_e32 v10, 1.0, v10
	v_add_f32_e32 v11, 1.0, v11
	v_add_f32_e32 v12, 1.0, v12
	v_add_f32_e32 v13, 1.0, v13
	v_add_f32_e32 v14, 1.0, v14
	v_add_f32_e32 v15, 1.0, v15
	v_rcp_f32_e32 v8, v8
	v_rcp_f32_e32 v9, v9
	v_rcp_f32_e32 v10, v10
	v_rcp_f32_e32 v11, v11
	v_rcp_f32_e32 v12, v12
	v_rcp_f32_e32 v13, v13
	v_rcp_f32_e32 v14, v14
	v_rcp_f32_e32 v15, v15
	v_mul_f32_e32 v8, v4, v8
	v_mul_f32_e32 v9, v5, v9
	v_mul_f32_e32 v10, v6, v10
	v_mul_f32_e32 v11, v7, v11
	v_mul_f32_e32 v12, v0, v12
	v_mul_f32_e32 v13, v1, v13
	v_mul_f32_e32 v14, v2, v14
	v_mul_f32_e32 v15, v3, v15
	v_cvt_pk_bf16_f32 v8, v8, v9
	v_cvt_pk_bf16_f32 v9, v10, v11
	v_cvt_pk_bf16_f32 v10, v12, v13
	v_cvt_pk_bf16_f32 v11, v14, v15
	global_store_dwordx4 v174, v[8:11], s[60:61] offset:256
	s_branch .Lwin_done
.Lwin_act2:
	v_mul_f32_e32 v128, 0xbfb8aa3b, v124
	v_mul_f32_e32 v129, 0xbfb8aa3b, v125
	v_mul_f32_e32 v130, 0xbfb8aa3b, v126
	v_mul_f32_e32 v131, 0xbfb8aa3b, v127
	v_mul_f32_e32 v132, 0xbfb8aa3b, v120
	v_mul_f32_e32 v133, 0xbfb8aa3b, v121
	v_mul_f32_e32 v134, 0xbfb8aa3b, v122
	v_mul_f32_e32 v135, 0xbfb8aa3b, v123
	v_exp_f32_e32 v128, v128
	v_exp_f32_e32 v129, v129
	v_exp_f32_e32 v130, v130
	v_exp_f32_e32 v131, v131
	v_exp_f32_e32 v132, v132
	v_exp_f32_e32 v133, v133
	v_exp_f32_e32 v134, v134
	v_exp_f32_e32 v135, v135
	v_add_f32_e32 v128, 1.0, v128
	v_add_f32_e32 v129, 1.0, v129
	v_add_f32_e32 v130, 1.0, v130
	v_add_f32_e32 v131, 1.0, v131
	v_add_f32_e32 v132, 1.0, v132
	v_add_f32_e32 v133, 1.0, v133
	v_add_f32_e32 v134, 1.0, v134
	v_add_f32_e32 v135, 1.0, v135
	v_rcp_f32_e32 v128, v128
	v_rcp_f32_e32 v129, v129
	v_rcp_f32_e32 v130, v130
	v_rcp_f32_e32 v131, v131
	v_rcp_f32_e32 v132, v132
	v_rcp_f32_e32 v133, v133
	v_rcp_f32_e32 v134, v134
	v_rcp_f32_e32 v135, v135
	s_nop 0
	v_cvt_pk_bf16_f32 v128, v128, v129
	v_cvt_pk_bf16_f32 v129, v130, v131
	v_cvt_pk_bf16_f32 v130, v132, v133
	v_cvt_pk_bf16_f32 v131, v134, v135
	global_store_dwordx4 v174, v[128:131], s[60:61]
	v_mul_f32_e32 v120, 0xbfb8aa3b, v116
	v_mul_f32_e32 v121, 0xbfb8aa3b, v117
	v_mul_f32_e32 v122, 0xbfb8aa3b, v118
	v_mul_f32_e32 v123, 0xbfb8aa3b, v119
	v_mul_f32_e32 v124, 0xbfb8aa3b, v112
	v_mul_f32_e32 v125, 0xbfb8aa3b, v113
	v_mul_f32_e32 v126, 0xbfb8aa3b, v114
	v_mul_f32_e32 v127, 0xbfb8aa3b, v115
	v_exp_f32_e32 v120, v120
	v_exp_f32_e32 v121, v121
	v_exp_f32_e32 v122, v122
	v_exp_f32_e32 v123, v123
	v_exp_f32_e32 v124, v124
	v_exp_f32_e32 v125, v125
	v_exp_f32_e32 v126, v126
	v_exp_f32_e32 v127, v127
	v_add_f32_e32 v120, 1.0, v120
	v_add_f32_e32 v121, 1.0, v121
	v_add_f32_e32 v122, 1.0, v122
	v_add_f32_e32 v123, 1.0, v123
	v_add_f32_e32 v124, 1.0, v124
	v_add_f32_e32 v125, 1.0, v125
	v_add_f32_e32 v126, 1.0, v126
	v_add_f32_e32 v127, 1.0, v127
	v_rcp_f32_e32 v120, v120
	v_rcp_f32_e32 v121, v121
	v_rcp_f32_e32 v122, v122
	v_rcp_f32_e32 v123, v123
	v_rcp_f32_e32 v124, v124
	v_rcp_f32_e32 v125, v125
	v_rcp_f32_e32 v126, v126
	v_rcp_f32_e32 v127, v127
	s_nop 0
	v_cvt_pk_bf16_f32 v120, v120, v121
	v_cvt_pk_bf16_f32 v121, v122, v123
	v_cvt_pk_bf16_f32 v122, v124, v125
	v_cvt_pk_bf16_f32 v123, v126, v127
	global_store_dwordx4 v174, v[120:123], s[60:61] offset:256
	s_add_u32 s60, s60, s64
	s_addc_u32 s61, s61, 0
	v_mul_f32_e32 v112, 0xbfb8aa3b, v108
	v_mul_f32_e32 v113, 0xbfb8aa3b, v109
	v_mul_f32_e32 v114, 0xbfb8aa3b, v110
	v_mul_f32_e32 v115, 0xbfb8aa3b, v111
	v_mul_f32_e32 v116, 0xbfb8aa3b, v104
	v_mul_f32_e32 v117, 0xbfb8aa3b, v105
	v_mul_f32_e32 v118, 0xbfb8aa3b, v106
	v_mul_f32_e32 v119, 0xbfb8aa3b, v107
	v_exp_f32_e32 v112, v112
	v_exp_f32_e32 v113, v113
	v_exp_f32_e32 v114, v114
	v_exp_f32_e32 v115, v115
	v_exp_f32_e32 v116, v116
	v_exp_f32_e32 v117, v117
	v_exp_f32_e32 v118, v118
	v_exp_f32_e32 v119, v119
	v_add_f32_e32 v112, 1.0, v112
	v_add_f32_e32 v113, 1.0, v113
	v_add_f32_e32 v114, 1.0, v114
	v_add_f32_e32 v115, 1.0, v115
	v_add_f32_e32 v116, 1.0, v116
	v_add_f32_e32 v117, 1.0, v117
	v_add_f32_e32 v118, 1.0, v118
	v_add_f32_e32 v119, 1.0, v119
	v_rcp_f32_e32 v112, v112
	v_rcp_f32_e32 v113, v113
	v_rcp_f32_e32 v114, v114
	v_rcp_f32_e32 v115, v115
	v_rcp_f32_e32 v116, v116
	v_rcp_f32_e32 v117, v117
	v_rcp_f32_e32 v118, v118
	v_rcp_f32_e32 v119, v119
	s_nop 0
	v_cvt_pk_bf16_f32 v112, v112, v113
	v_cvt_pk_bf16_f32 v113, v114, v115
	v_cvt_pk_bf16_f32 v114, v116, v117
	v_cvt_pk_bf16_f32 v115, v118, v119
	global_store_dwordx4 v174, v[112:115], s[60:61]
	v_mul_f32_e32 v104, 0xbfb8aa3b, v100
	v_mul_f32_e32 v105, 0xbfb8aa3b, v101
	v_mul_f32_e32 v106, 0xbfb8aa3b, v102
	v_mul_f32_e32 v107, 0xbfb8aa3b, v103
	v_mul_f32_e32 v108, 0xbfb8aa3b, v96
	v_mul_f32_e32 v109, 0xbfb8aa3b, v97
	v_mul_f32_e32 v110, 0xbfb8aa3b, v98
	v_mul_f32_e32 v111, 0xbfb8aa3b, v99
	v_exp_f32_e32 v104, v104
	v_exp_f32_e32 v105, v105
	v_exp_f32_e32 v106, v106
	v_exp_f32_e32 v107, v107
	v_exp_f32_e32 v108, v108
	v_exp_f32_e32 v109, v109
	v_exp_f32_e32 v110, v110
	v_exp_f32_e32 v111, v111
	v_add_f32_e32 v104, 1.0, v104
	v_add_f32_e32 v105, 1.0, v105
	v_add_f32_e32 v106, 1.0, v106
	v_add_f32_e32 v107, 1.0, v107
	v_add_f32_e32 v108, 1.0, v108
	v_add_f32_e32 v109, 1.0, v109
	v_add_f32_e32 v110, 1.0, v110
	v_add_f32_e32 v111, 1.0, v111
	v_rcp_f32_e32 v104, v104
	v_rcp_f32_e32 v105, v105
	v_rcp_f32_e32 v106, v106
	v_rcp_f32_e32 v107, v107
	v_rcp_f32_e32 v108, v108
	v_rcp_f32_e32 v109, v109
	v_rcp_f32_e32 v110, v110
	v_rcp_f32_e32 v111, v111
	s_nop 0
	v_cvt_pk_bf16_f32 v104, v104, v105
	v_cvt_pk_bf16_f32 v105, v106, v107
	v_cvt_pk_bf16_f32 v106, v108, v109
	v_cvt_pk_bf16_f32 v107, v110, v111
	global_store_dwordx4 v174, v[104:107], s[60:61] offset:256
	s_add_u32 s60, s60, s64
	s_addc_u32 s61, s61, 0
	v_mul_f32_e32 v96, 0xbfb8aa3b, v92
	v_mul_f32_e32 v97, 0xbfb8aa3b, v93
	v_mul_f32_e32 v98, 0xbfb8aa3b, v94
	v_mul_f32_e32 v99, 0xbfb8aa3b, v95
	v_mul_f32_e32 v100, 0xbfb8aa3b, v88
	v_mul_f32_e32 v101, 0xbfb8aa3b, v89
	v_mul_f32_e32 v102, 0xbfb8aa3b, v90
	v_mul_f32_e32 v103, 0xbfb8aa3b, v91
	v_exp_f32_e32 v96, v96
	v_exp_f32_e32 v97, v97
	v_exp_f32_e32 v98, v98
	v_exp_f32_e32 v99, v99
	v_exp_f32_e32 v100, v100
	v_exp_f32_e32 v101, v101
	v_exp_f32_e32 v102, v102
	v_exp_f32_e32 v103, v103
	v_add_f32_e32 v96, 1.0, v96
	v_add_f32_e32 v97, 1.0, v97
	v_add_f32_e32 v98, 1.0, v98
	v_add_f32_e32 v99, 1.0, v99
	v_add_f32_e32 v100, 1.0, v100
	v_add_f32_e32 v101, 1.0, v101
	v_add_f32_e32 v102, 1.0, v102
	v_add_f32_e32 v103, 1.0, v103
	v_rcp_f32_e32 v96, v96
	v_rcp_f32_e32 v97, v97
	v_rcp_f32_e32 v98, v98
	v_rcp_f32_e32 v99, v99
	v_rcp_f32_e32 v100, v100
	v_rcp_f32_e32 v101, v101
	v_rcp_f32_e32 v102, v102
	v_rcp_f32_e32 v103, v103
	s_nop 0
	v_cvt_pk_bf16_f32 v96, v96, v97
	v_cvt_pk_bf16_f32 v97, v98, v99
	v_cvt_pk_bf16_f32 v98, v100, v101
	v_cvt_pk_bf16_f32 v99, v102, v103
	global_store_dwordx4 v174, v[96:99], s[60:61]
	v_mul_f32_e32 v88, 0xbfb8aa3b, v84
	v_mul_f32_e32 v89, 0xbfb8aa3b, v85
	v_mul_f32_e32 v90, 0xbfb8aa3b, v86
	v_mul_f32_e32 v91, 0xbfb8aa3b, v87
	v_mul_f32_e32 v92, 0xbfb8aa3b, v80
	v_mul_f32_e32 v93, 0xbfb8aa3b, v81
	v_mul_f32_e32 v94, 0xbfb8aa3b, v82
	v_mul_f32_e32 v95, 0xbfb8aa3b, v83
	v_exp_f32_e32 v88, v88
	v_exp_f32_e32 v89, v89
	v_exp_f32_e32 v90, v90
	v_exp_f32_e32 v91, v91
	v_exp_f32_e32 v92, v92
	v_exp_f32_e32 v93, v93
	v_exp_f32_e32 v94, v94
	v_exp_f32_e32 v95, v95
	v_add_f32_e32 v88, 1.0, v88
	v_add_f32_e32 v89, 1.0, v89
	v_add_f32_e32 v90, 1.0, v90
	v_add_f32_e32 v91, 1.0, v91
	v_add_f32_e32 v92, 1.0, v92
	v_add_f32_e32 v93, 1.0, v93
	v_add_f32_e32 v94, 1.0, v94
	v_add_f32_e32 v95, 1.0, v95
	v_rcp_f32_e32 v88, v88
	v_rcp_f32_e32 v89, v89
	v_rcp_f32_e32 v90, v90
	v_rcp_f32_e32 v91, v91
	v_rcp_f32_e32 v92, v92
	v_rcp_f32_e32 v93, v93
	v_rcp_f32_e32 v94, v94
	v_rcp_f32_e32 v95, v95
	s_nop 0
	v_cvt_pk_bf16_f32 v88, v88, v89
	v_cvt_pk_bf16_f32 v89, v90, v91
	v_cvt_pk_bf16_f32 v90, v92, v93
	v_cvt_pk_bf16_f32 v91, v94, v95
	global_store_dwordx4 v174, v[88:91], s[60:61] offset:256
	s_add_u32 s60, s60, s64
	s_addc_u32 s61, s61, 0
	v_mul_f32_e32 v80, 0xbfb8aa3b, v76
	v_mul_f32_e32 v81, 0xbfb8aa3b, v77
	v_mul_f32_e32 v82, 0xbfb8aa3b, v78
	v_mul_f32_e32 v83, 0xbfb8aa3b, v79
	v_mul_f32_e32 v84, 0xbfb8aa3b, v72
	v_mul_f32_e32 v85, 0xbfb8aa3b, v73
	v_mul_f32_e32 v86, 0xbfb8aa3b, v74
	v_mul_f32_e32 v87, 0xbfb8aa3b, v75
	v_exp_f32_e32 v80, v80
	v_exp_f32_e32 v81, v81
	v_exp_f32_e32 v82, v82
	v_exp_f32_e32 v83, v83
	v_exp_f32_e32 v84, v84
	v_exp_f32_e32 v85, v85
	v_exp_f32_e32 v86, v86
	v_exp_f32_e32 v87, v87
	v_add_f32_e32 v80, 1.0, v80
	v_add_f32_e32 v81, 1.0, v81
	v_add_f32_e32 v82, 1.0, v82
	v_add_f32_e32 v83, 1.0, v83
	v_add_f32_e32 v84, 1.0, v84
	v_add_f32_e32 v85, 1.0, v85
	v_add_f32_e32 v86, 1.0, v86
	v_add_f32_e32 v87, 1.0, v87
	v_rcp_f32_e32 v80, v80
	v_rcp_f32_e32 v81, v81
	v_rcp_f32_e32 v82, v82
	v_rcp_f32_e32 v83, v83
	v_rcp_f32_e32 v84, v84
	v_rcp_f32_e32 v85, v85
	v_rcp_f32_e32 v86, v86
	v_rcp_f32_e32 v87, v87
	s_nop 0
	v_cvt_pk_bf16_f32 v80, v80, v81
	v_cvt_pk_bf16_f32 v81, v82, v83
	v_cvt_pk_bf16_f32 v82, v84, v85
	v_cvt_pk_bf16_f32 v83, v86, v87
	global_store_dwordx4 v174, v[80:83], s[60:61]
	v_mul_f32_e32 v72, 0xbfb8aa3b, v68
	v_mul_f32_e32 v73, 0xbfb8aa3b, v69
	v_mul_f32_e32 v74, 0xbfb8aa3b, v70
	v_mul_f32_e32 v75, 0xbfb8aa3b, v71
	v_mul_f32_e32 v76, 0xbfb8aa3b, v64
	v_mul_f32_e32 v77, 0xbfb8aa3b, v65
	v_mul_f32_e32 v78, 0xbfb8aa3b, v66
	v_mul_f32_e32 v79, 0xbfb8aa3b, v67
	v_exp_f32_e32 v72, v72
	v_exp_f32_e32 v73, v73
	v_exp_f32_e32 v74, v74
	v_exp_f32_e32 v75, v75
	v_exp_f32_e32 v76, v76
	v_exp_f32_e32 v77, v77
	v_exp_f32_e32 v78, v78
	v_exp_f32_e32 v79, v79
	v_add_f32_e32 v72, 1.0, v72
	v_add_f32_e32 v73, 1.0, v73
	v_add_f32_e32 v74, 1.0, v74
	v_add_f32_e32 v75, 1.0, v75
	v_add_f32_e32 v76, 1.0, v76
	v_add_f32_e32 v77, 1.0, v77
	v_add_f32_e32 v78, 1.0, v78
	v_add_f32_e32 v79, 1.0, v79
	v_rcp_f32_e32 v72, v72
	v_rcp_f32_e32 v73, v73
	v_rcp_f32_e32 v74, v74
	v_rcp_f32_e32 v75, v75
	v_rcp_f32_e32 v76, v76
	v_rcp_f32_e32 v77, v77
	v_rcp_f32_e32 v78, v78
	v_rcp_f32_e32 v79, v79
	s_nop 0
	v_cvt_pk_bf16_f32 v72, v72, v73
	v_cvt_pk_bf16_f32 v73, v74, v75
	v_cvt_pk_bf16_f32 v74, v76, v77
	v_cvt_pk_bf16_f32 v75, v78, v79
	global_store_dwordx4 v174, v[72:75], s[60:61] offset:256
	s_add_u32 s60, s60, s64
	s_addc_u32 s61, s61, 0
	s_add_u32 s60, s60, s65
	s_addc_u32 s61, s61, 0
	v_mul_f32_e32 v64, 0xbfb8aa3b, v60
	v_mul_f32_e32 v65, 0xbfb8aa3b, v61
	v_mul_f32_e32 v66, 0xbfb8aa3b, v62
	v_mul_f32_e32 v67, 0xbfb8aa3b, v63
	v_mul_f32_e32 v68, 0xbfb8aa3b, v56
	v_mul_f32_e32 v69, 0xbfb8aa3b, v57
	v_mul_f32_e32 v70, 0xbfb8aa3b, v58
	v_mul_f32_e32 v71, 0xbfb8aa3b, v59
	v_exp_f32_e32 v64, v64
	v_exp_f32_e32 v65, v65
	v_exp_f32_e32 v66, v66
	v_exp_f32_e32 v67, v67
	v_exp_f32_e32 v68, v68
	v_exp_f32_e32 v69, v69
	v_exp_f32_e32 v70, v70
	v_exp_f32_e32 v71, v71
	v_add_f32_e32 v64, 1.0, v64
	v_add_f32_e32 v65, 1.0, v65
	v_add_f32_e32 v66, 1.0, v66
	v_add_f32_e32 v67, 1.0, v67
	v_add_f32_e32 v68, 1.0, v68
	v_add_f32_e32 v69, 1.0, v69
	v_add_f32_e32 v70, 1.0, v70
	v_add_f32_e32 v71, 1.0, v71
	v_rcp_f32_e32 v64, v64
	v_rcp_f32_e32 v65, v65
	v_rcp_f32_e32 v66, v66
	v_rcp_f32_e32 v67, v67
	v_rcp_f32_e32 v68, v68
	v_rcp_f32_e32 v69, v69
	v_rcp_f32_e32 v70, v70
	v_rcp_f32_e32 v71, v71
	s_nop 0
	v_cvt_pk_bf16_f32 v64, v64, v65
	v_cvt_pk_bf16_f32 v65, v66, v67
	v_cvt_pk_bf16_f32 v66, v68, v69
	v_cvt_pk_bf16_f32 v67, v70, v71
	global_store_dwordx4 v174, v[64:67], s[60:61]
	v_mul_f32_e32 v56, 0xbfb8aa3b, v52
	v_mul_f32_e32 v57, 0xbfb8aa3b, v53
	v_mul_f32_e32 v58, 0xbfb8aa3b, v54
	v_mul_f32_e32 v59, 0xbfb8aa3b, v55
	v_mul_f32_e32 v60, 0xbfb8aa3b, v48
	v_mul_f32_e32 v61, 0xbfb8aa3b, v49
	v_mul_f32_e32 v62, 0xbfb8aa3b, v50
	v_mul_f32_e32 v63, 0xbfb8aa3b, v51
	v_exp_f32_e32 v56, v56
	v_exp_f32_e32 v57, v57
	v_exp_f32_e32 v58, v58
	v_exp_f32_e32 v59, v59
	v_exp_f32_e32 v60, v60
	v_exp_f32_e32 v61, v61
	v_exp_f32_e32 v62, v62
	v_exp_f32_e32 v63, v63
	v_add_f32_e32 v56, 1.0, v56
	v_add_f32_e32 v57, 1.0, v57
	v_add_f32_e32 v58, 1.0, v58
	v_add_f32_e32 v59, 1.0, v59
	v_add_f32_e32 v60, 1.0, v60
	v_add_f32_e32 v61, 1.0, v61
	v_add_f32_e32 v62, 1.0, v62
	v_add_f32_e32 v63, 1.0, v63
	v_rcp_f32_e32 v56, v56
	v_rcp_f32_e32 v57, v57
	v_rcp_f32_e32 v58, v58
	v_rcp_f32_e32 v59, v59
	v_rcp_f32_e32 v60, v60
	v_rcp_f32_e32 v61, v61
	v_rcp_f32_e32 v62, v62
	v_rcp_f32_e32 v63, v63
	s_nop 0
	v_cvt_pk_bf16_f32 v56, v56, v57
	v_cvt_pk_bf16_f32 v57, v58, v59
	v_cvt_pk_bf16_f32 v58, v60, v61
	v_cvt_pk_bf16_f32 v59, v62, v63
	global_store_dwordx4 v174, v[56:59], s[60:61] offset:256
	s_add_u32 s60, s60, s64
	s_addc_u32 s61, s61, 0
	v_mul_f32_e32 v48, 0xbfb8aa3b, v44
	v_mul_f32_e32 v49, 0xbfb8aa3b, v45
	v_mul_f32_e32 v50, 0xbfb8aa3b, v46
	v_mul_f32_e32 v51, 0xbfb8aa3b, v47
	v_mul_f32_e32 v52, 0xbfb8aa3b, v40
	v_mul_f32_e32 v53, 0xbfb8aa3b, v41
	v_mul_f32_e32 v54, 0xbfb8aa3b, v42
	v_mul_f32_e32 v55, 0xbfb8aa3b, v43
	v_exp_f32_e32 v48, v48
	v_exp_f32_e32 v49, v49
	v_exp_f32_e32 v50, v50
	v_exp_f32_e32 v51, v51
	v_exp_f32_e32 v52, v52
	v_exp_f32_e32 v53, v53
	v_exp_f32_e32 v54, v54
	v_exp_f32_e32 v55, v55
	v_add_f32_e32 v48, 1.0, v48
	v_add_f32_e32 v49, 1.0, v49
	v_add_f32_e32 v50, 1.0, v50
	v_add_f32_e32 v51, 1.0, v51
	v_add_f32_e32 v52, 1.0, v52
	v_add_f32_e32 v53, 1.0, v53
	v_add_f32_e32 v54, 1.0, v54
	v_add_f32_e32 v55, 1.0, v55
	v_rcp_f32_e32 v48, v48
	v_rcp_f32_e32 v49, v49
	v_rcp_f32_e32 v50, v50
	v_rcp_f32_e32 v51, v51
	v_rcp_f32_e32 v52, v52
	v_rcp_f32_e32 v53, v53
	v_rcp_f32_e32 v54, v54
	v_rcp_f32_e32 v55, v55
	s_nop 0
	v_cvt_pk_bf16_f32 v48, v48, v49
	v_cvt_pk_bf16_f32 v49, v50, v51
	v_cvt_pk_bf16_f32 v50, v52, v53
	v_cvt_pk_bf16_f32 v51, v54, v55
	global_store_dwordx4 v174, v[48:51], s[60:61]
	v_mul_f32_e32 v40, 0xbfb8aa3b, v36
	v_mul_f32_e32 v41, 0xbfb8aa3b, v37
	v_mul_f32_e32 v42, 0xbfb8aa3b, v38
	v_mul_f32_e32 v43, 0xbfb8aa3b, v39
	v_mul_f32_e32 v44, 0xbfb8aa3b, v32
	v_mul_f32_e32 v45, 0xbfb8aa3b, v33
	v_mul_f32_e32 v46, 0xbfb8aa3b, v34
	v_mul_f32_e32 v47, 0xbfb8aa3b, v35
	v_exp_f32_e32 v40, v40
	v_exp_f32_e32 v41, v41
	v_exp_f32_e32 v42, v42
	v_exp_f32_e32 v43, v43
	v_exp_f32_e32 v44, v44
	v_exp_f32_e32 v45, v45
	v_exp_f32_e32 v46, v46
	v_exp_f32_e32 v47, v47
	v_add_f32_e32 v40, 1.0, v40
	v_add_f32_e32 v41, 1.0, v41
	v_add_f32_e32 v42, 1.0, v42
	v_add_f32_e32 v43, 1.0, v43
	v_add_f32_e32 v44, 1.0, v44
	v_add_f32_e32 v45, 1.0, v45
	v_add_f32_e32 v46, 1.0, v46
	v_add_f32_e32 v47, 1.0, v47
	v_rcp_f32_e32 v40, v40
	v_rcp_f32_e32 v41, v41
	v_rcp_f32_e32 v42, v42
	v_rcp_f32_e32 v43, v43
	v_rcp_f32_e32 v44, v44
	v_rcp_f32_e32 v45, v45
	v_rcp_f32_e32 v46, v46
	v_rcp_f32_e32 v47, v47
	s_nop 0
	v_cvt_pk_bf16_f32 v40, v40, v41
	v_cvt_pk_bf16_f32 v41, v42, v43
	v_cvt_pk_bf16_f32 v42, v44, v45
	v_cvt_pk_bf16_f32 v43, v46, v47
	global_store_dwordx4 v174, v[40:43], s[60:61] offset:256
	s_add_u32 s60, s60, s64
	s_addc_u32 s61, s61, 0
	v_mul_f32_e32 v32, 0xbfb8aa3b, v28
	v_mul_f32_e32 v33, 0xbfb8aa3b, v29
	v_mul_f32_e32 v34, 0xbfb8aa3b, v30
	v_mul_f32_e32 v35, 0xbfb8aa3b, v31
	v_mul_f32_e32 v36, 0xbfb8aa3b, v24
	v_mul_f32_e32 v37, 0xbfb8aa3b, v25
	v_mul_f32_e32 v38, 0xbfb8aa3b, v26
	v_mul_f32_e32 v39, 0xbfb8aa3b, v27
	v_exp_f32_e32 v32, v32
	v_exp_f32_e32 v33, v33
	v_exp_f32_e32 v34, v34
	v_exp_f32_e32 v35, v35
	v_exp_f32_e32 v36, v36
	v_exp_f32_e32 v37, v37
	v_exp_f32_e32 v38, v38
	v_exp_f32_e32 v39, v39
	v_add_f32_e32 v32, 1.0, v32
	v_add_f32_e32 v33, 1.0, v33
	v_add_f32_e32 v34, 1.0, v34
	v_add_f32_e32 v35, 1.0, v35
	v_add_f32_e32 v36, 1.0, v36
	v_add_f32_e32 v37, 1.0, v37
	v_add_f32_e32 v38, 1.0, v38
	v_add_f32_e32 v39, 1.0, v39
	v_rcp_f32_e32 v32, v32
	v_rcp_f32_e32 v33, v33
	v_rcp_f32_e32 v34, v34
	v_rcp_f32_e32 v35, v35
	v_rcp_f32_e32 v36, v36
	v_rcp_f32_e32 v37, v37
	v_rcp_f32_e32 v38, v38
	v_rcp_f32_e32 v39, v39
	s_nop 0
	v_cvt_pk_bf16_f32 v32, v32, v33
	v_cvt_pk_bf16_f32 v33, v34, v35
	v_cvt_pk_bf16_f32 v34, v36, v37
	v_cvt_pk_bf16_f32 v35, v38, v39
	global_store_dwordx4 v174, v[32:35], s[60:61]
	v_mul_f32_e32 v24, 0xbfb8aa3b, v20
	v_mul_f32_e32 v25, 0xbfb8aa3b, v21
	v_mul_f32_e32 v26, 0xbfb8aa3b, v22
	v_mul_f32_e32 v27, 0xbfb8aa3b, v23
	v_mul_f32_e32 v28, 0xbfb8aa3b, v16
	v_mul_f32_e32 v29, 0xbfb8aa3b, v17
	v_mul_f32_e32 v30, 0xbfb8aa3b, v18
	v_mul_f32_e32 v31, 0xbfb8aa3b, v19
	v_exp_f32_e32 v24, v24
	v_exp_f32_e32 v25, v25
	v_exp_f32_e32 v26, v26
	v_exp_f32_e32 v27, v27
	v_exp_f32_e32 v28, v28
	v_exp_f32_e32 v29, v29
	v_exp_f32_e32 v30, v30
	v_exp_f32_e32 v31, v31
	v_add_f32_e32 v24, 1.0, v24
	v_add_f32_e32 v25, 1.0, v25
	v_add_f32_e32 v26, 1.0, v26
	v_add_f32_e32 v27, 1.0, v27
	v_add_f32_e32 v28, 1.0, v28
	v_add_f32_e32 v29, 1.0, v29
	v_add_f32_e32 v30, 1.0, v30
	v_add_f32_e32 v31, 1.0, v31
	v_rcp_f32_e32 v24, v24
	v_rcp_f32_e32 v25, v25
	v_rcp_f32_e32 v26, v26
	v_rcp_f32_e32 v27, v27
	v_rcp_f32_e32 v28, v28
	v_rcp_f32_e32 v29, v29
	v_rcp_f32_e32 v30, v30
	v_rcp_f32_e32 v31, v31
	s_nop 0
	v_cvt_pk_bf16_f32 v24, v24, v25
	v_cvt_pk_bf16_f32 v25, v26, v27
	v_cvt_pk_bf16_f32 v26, v28, v29
	v_cvt_pk_bf16_f32 v27, v30, v31
	global_store_dwordx4 v174, v[24:27], s[60:61] offset:256
	s_add_u32 s60, s60, s64
	s_addc_u32 s61, s61, 0
	v_mul_f32_e32 v16, 0xbfb8aa3b, v12
	v_mul_f32_e32 v17, 0xbfb8aa3b, v13
	v_mul_f32_e32 v18, 0xbfb8aa3b, v14
	v_mul_f32_e32 v19, 0xbfb8aa3b, v15
	v_mul_f32_e32 v20, 0xbfb8aa3b, v8
	v_mul_f32_e32 v21, 0xbfb8aa3b, v9
	v_mul_f32_e32 v22, 0xbfb8aa3b, v10
	v_mul_f32_e32 v23, 0xbfb8aa3b, v11
	v_exp_f32_e32 v16, v16
	v_exp_f32_e32 v17, v17
	v_exp_f32_e32 v18, v18
	v_exp_f32_e32 v19, v19
	v_exp_f32_e32 v20, v20
	v_exp_f32_e32 v21, v21
	v_exp_f32_e32 v22, v22
	v_exp_f32_e32 v23, v23
	v_add_f32_e32 v16, 1.0, v16
	v_add_f32_e32 v17, 1.0, v17
	v_add_f32_e32 v18, 1.0, v18
	v_add_f32_e32 v19, 1.0, v19
	v_add_f32_e32 v20, 1.0, v20
	v_add_f32_e32 v21, 1.0, v21
	v_add_f32_e32 v22, 1.0, v22
	v_add_f32_e32 v23, 1.0, v23
	v_rcp_f32_e32 v16, v16
	v_rcp_f32_e32 v17, v17
	v_rcp_f32_e32 v18, v18
	v_rcp_f32_e32 v19, v19
	v_rcp_f32_e32 v20, v20
	v_rcp_f32_e32 v21, v21
	v_rcp_f32_e32 v22, v22
	v_rcp_f32_e32 v23, v23
	s_nop 0
	v_cvt_pk_bf16_f32 v16, v16, v17
	v_cvt_pk_bf16_f32 v17, v18, v19
	v_cvt_pk_bf16_f32 v18, v20, v21
	v_cvt_pk_bf16_f32 v19, v22, v23
	global_store_dwordx4 v174, v[16:19], s[60:61]
	v_mul_f32_e32 v8, 0xbfb8aa3b, v4
	v_mul_f32_e32 v9, 0xbfb8aa3b, v5
	v_mul_f32_e32 v10, 0xbfb8aa3b, v6
	v_mul_f32_e32 v11, 0xbfb8aa3b, v7
	v_mul_f32_e32 v12, 0xbfb8aa3b, v0
	v_mul_f32_e32 v13, 0xbfb8aa3b, v1
	v_mul_f32_e32 v14, 0xbfb8aa3b, v2
	v_mul_f32_e32 v15, 0xbfb8aa3b, v3
	v_exp_f32_e32 v8, v8
	v_exp_f32_e32 v9, v9
	v_exp_f32_e32 v10, v10
	v_exp_f32_e32 v11, v11
	v_exp_f32_e32 v12, v12
	v_exp_f32_e32 v13, v13
	v_exp_f32_e32 v14, v14
	v_exp_f32_e32 v15, v15
	v_add_f32_e32 v8, 1.0, v8
	v_add_f32_e32 v9, 1.0, v9
	v_add_f32_e32 v10, 1.0, v10
	v_add_f32_e32 v11, 1.0, v11
	v_add_f32_e32 v12, 1.0, v12
	v_add_f32_e32 v13, 1.0, v13
	v_add_f32_e32 v14, 1.0, v14
	v_add_f32_e32 v15, 1.0, v15
	v_rcp_f32_e32 v8, v8
	v_rcp_f32_e32 v9, v9
	v_rcp_f32_e32 v10, v10
	v_rcp_f32_e32 v11, v11
	v_rcp_f32_e32 v12, v12
	v_rcp_f32_e32 v13, v13
	v_rcp_f32_e32 v14, v14
	v_rcp_f32_e32 v15, v15
	s_nop 0
	v_cvt_pk_bf16_f32 v8, v8, v9
	v_cvt_pk_bf16_f32 v9, v10, v11
	v_cvt_pk_bf16_f32 v10, v12, v13
	v_cvt_pk_bf16_f32 v11, v14, v15
	global_store_dwordx4 v174, v[8:11], s[60:61] offset:256
	s_branch .Lwin_done

.Lwin_done:
	s_andn2_b64 vcc, exec, s[8:9]
	s_mov_b64 s[8:9], -1
	s_cbranch_vccnz .LBB0_363
	s_andn2_b64 vcc, exec, s[26:27]
	s_cbranch_vccnz .LBB0_362
	s_barrier
	s_branch .LBB0_362

.LBB0_820:
	s_add_i32 s40, s8, -3
	s_min_i32 s9, s40, s7
	s_waitcnt vmcnt(13)
	v_lshl_add_u32 v56, s9, 8, v102
	v_ashrrev_i32_e32 v57, 31, v56
	v_lshlrev_b64 v[56:57], 7, v[56:57]
	s_waitcnt vmcnt(12)
	v_lshl_add_u64 v[60:61], v[100:101], 0, v[56:57]
	global_load_dwordx4 v[88:91], v[60:61], off
	global_load_dwordx4 v[92:95], v[60:61], off offset:1024
	global_load_dwordx4 v[56:59], v[60:61], off offset:2048
	s_nop 0
	global_load_dwordx4 v[60:63], v[60:61], off offset:3072
	v_add_u32_e32 v103, v178, v98
	s_waitcnt vmcnt(15)
	ds_write_b128 v103, v[64:67]
	s_waitcnt vmcnt(14)
	ds_write_b128 v103, v[68:71] offset:1152
	v_add_u32_e32 v107, v179, v96
	ds_read_b128 v[64:67], v107
	ds_read_b128 v[68:71], v107 offset:64
	s_waitcnt vmcnt(13)
	ds_write_b128 v103, v[32:35]
	s_waitcnt vmcnt(12)
	ds_write_b128 v103, v[36:39] offset:1152
	ds_read_b128 v[32:35], v107
	ds_read_b128 v[36:39], v107 offset:64
	s_waitcnt lgkmcnt(5)
	v_mfma_f32_16x16x32_bf16 v[108:111], v[0:3], v[64:67], 0
	v_mfma_f32_16x16x32_bf16 v[112:115], v[8:11], v[64:67], 0
	s_waitcnt lgkmcnt(4)
	v_mfma_f32_16x16x32_bf16 v[108:111], v[4:7], v[68:71], v[108:111]
	v_mfma_f32_16x16x32_bf16 v[112:115], v[12:15], v[68:71], v[112:115]
	v_mfma_f32_16x16x32_bf16 v[116:119], v[16:19], v[64:67], 0
	s_nop 5
	v_max_f32_e32 v108, 0, v108
	v_fma_f32 v120, v162, v108, 0
	v_max_f32_e32 v108, 0, v109
	v_max_f32_e32 v112, 0, v112
	v_fmac_f32_e32 v120, v163, v108
	v_fma_f32 v112, v166, v112, 0
	v_max_f32_e32 v108, 0, v113
	v_fmac_f32_e32 v112, v167, v108
	v_max_f32_e32 v108, 0, v110
	v_fmac_f32_e32 v120, v164, v108
	v_mfma_f32_16x16x32_bf16 v[64:67], v[24:27], v[64:67], 0
	v_max_f32_e32 v108, 0, v114
	v_fmac_f32_e32 v112, v168, v108
	v_max_f32_e32 v108, 0, v111
	v_fmac_f32_e32 v120, v165, v108
	v_mfma_f32_16x16x32_bf16 v[64:67], v[28:31], v[68:71], v[64:67]
	v_max_f32_e32 v113, 0, v115
	v_fmac_f32_e32 v112, v169, v113
	v_add_f32_e32 v112, v120, v112
	v_mfma_f32_16x16x32_bf16 v[108:111], v[20:23], v[68:71], v[116:119]
	ds_write_b32 v99, v112
	s_nop 2
	v_max_f32_e32 v64, 0, v64
	v_fma_f32 v64, v174, v64, 0
	s_nop 1
	v_max_f32_e32 v68, 0, v108
	v_max_f32_e32 v65, 0, v65
	v_fma_f32 v68, v170, v68, 0
	v_max_f32_e32 v69, 0, v109
	v_fmac_f32_e32 v64, v175, v65
	v_fmac_f32_e32 v68, v171, v69
	v_max_f32_e32 v65, 0, v110
	v_fmac_f32_e32 v68, v172, v65
	v_max_f32_e32 v65, 0, v66
	v_fmac_f32_e32 v64, v176, v65
	v_max_f32_e32 v65, 0, v111
	v_fmac_f32_e32 v68, v173, v65
	v_max_f32_e32 v65, 0, v67
	v_fmac_f32_e32 v64, v177, v65
	v_add_f32_e32 v64, v68, v64
	v_add_u32_e32 v65, 0x10000, v99
	ds_write_b32 v65, v64
	s_waitcnt lgkmcnt(3)
	v_mfma_f32_16x16x32_bf16 v[64:67], v[0:3], v[32:35], 0
	v_mfma_f32_16x16x32_bf16 v[68:71], v[8:11], v[32:35], 0
	s_waitcnt lgkmcnt(2)
	v_mfma_f32_16x16x32_bf16 v[64:67], v[4:7], v[36:39], v[64:67]
	v_mfma_f32_16x16x32_bf16 v[68:71], v[12:15], v[36:39], v[68:71]
	v_mfma_f32_16x16x32_bf16 v[108:111], v[16:19], v[32:35], 0
	s_nop 5
	v_max_f32_e32 v64, 0, v64
	v_fma_f32 v112, v162, v64, 0
	v_max_f32_e32 v64, 0, v68
	v_fma_f32 v68, v166, v64, 0
	v_max_f32_e32 v64, 0, v65
	v_fmac_f32_e32 v112, v163, v64
	v_max_f32_e32 v64, 0, v69
	v_fmac_f32_e32 v68, v167, v64
	v_max_f32_e32 v64, 0, v66
	v_fmac_f32_e32 v112, v164, v64
	v_mfma_f32_16x16x32_bf16 v[32:35], v[24:27], v[32:35], 0
	v_max_f32_e32 v64, 0, v70
	v_fmac_f32_e32 v68, v168, v64
	v_max_f32_e32 v64, 0, v67
	v_fmac_f32_e32 v112, v165, v64
	v_mfma_f32_16x16x32_bf16 v[32:35], v[28:31], v[36:39], v[32:35]
	v_max_f32_e32 v69, 0, v71
	v_fmac_f32_e32 v68, v169, v69
	v_add_f32_e32 v68, v112, v68
	v_mfma_f32_16x16x32_bf16 v[64:67], v[20:23], v[36:39], v[108:111]
	ds_write_b32 v99, v68 offset:64
	s_nop 2
	v_max_f32_e32 v32, 0, v32
	v_fma_f32 v32, v174, v32, 0
	s_nop 1
	v_max_f32_e32 v36, 0, v64
	v_max_f32_e32 v33, 0, v33
	v_fma_f32 v36, v170, v36, 0
	v_max_f32_e32 v37, 0, v65
	v_fmac_f32_e32 v32, v175, v33
	v_fmac_f32_e32 v36, v171, v37
	v_max_f32_e32 v33, 0, v66
	v_fmac_f32_e32 v36, v172, v33
	v_max_f32_e32 v33, 0, v34
	v_fmac_f32_e32 v32, v176, v33
	v_max_f32_e32 v33, 0, v67
	v_fmac_f32_e32 v36, v173, v33
	v_max_f32_e32 v33, 0, v35
	v_fmac_f32_e32 v32, v177, v33
	v_add_f32_e32 v32, v36, v32
	v_add_u32_e32 v33, 0x10040, v99
	ds_write_b32 v33, v32
	s_add_i32 s9, s8, -2
	s_min_i32 s57, s9, s7
	v_lshl_add_u32 v32, s57, 8, v102
	v_ashrrev_i32_e32 v33, 31, v32
	v_lshlrev_b64 v[32:33], 7, v[32:33]
	v_lshl_add_u64 v[36:37], v[100:101], 0, v[32:33]
	global_load_dwordx4 v[64:67], v[36:37], off
	global_load_dwordx4 v[68:71], v[36:37], off offset:1024
	global_load_dwordx4 v[32:35], v[36:37], off offset:2048
	s_nop 0
	global_load_dwordx4 v[36:39], v[36:37], off offset:3072
	s_add_i32 s57, s8, -5
	s_cmp_ge_i32 s57, s6
	s_cbranch_scc1 .LBB0_822
	s_waitcnt vmcnt(15)
	ds_write_b128 v103, v[72:75]
	s_waitcnt vmcnt(14)
	ds_write_b128 v103, v[76:79] offset:1152
	ds_read_b128 v[72:75], v107
	ds_read_b128 v[76:79], v107 offset:64
	s_waitcnt vmcnt(13)
	ds_write_b128 v103, v[40:43]
	s_waitcnt vmcnt(12)
	ds_write_b128 v103, v[44:47] offset:1152
	ds_read_b128 v[40:43], v107
	ds_read_b128 v[44:47], v107 offset:64
	s_waitcnt lgkmcnt(5)
	v_mfma_f32_16x16x32_bf16 v[108:111], v[0:3], v[72:75], 0
	v_mfma_f32_16x16x32_bf16 v[112:115], v[8:11], v[72:75], 0
	s_waitcnt lgkmcnt(4)
	v_mfma_f32_16x16x32_bf16 v[108:111], v[4:7], v[76:79], v[108:111]
	v_mfma_f32_16x16x32_bf16 v[112:115], v[12:15], v[76:79], v[112:115]
	v_mfma_f32_16x16x32_bf16 v[116:119], v[16:19], v[72:75], 0
	s_nop 5
	v_max_f32_e32 v108, 0, v108
	v_fma_f32 v120, v162, v108, 0
	v_max_f32_e32 v108, 0, v109
	v_max_f32_e32 v112, 0, v112
	v_fmac_f32_e32 v120, v163, v108
	v_fma_f32 v112, v166, v112, 0
	v_max_f32_e32 v108, 0, v113
	v_fmac_f32_e32 v112, v167, v108
	v_max_f32_e32 v108, 0, v110
	v_fmac_f32_e32 v120, v164, v108
	v_mfma_f32_16x16x32_bf16 v[72:75], v[24:27], v[72:75], 0
	v_max_f32_e32 v108, 0, v114
	v_fmac_f32_e32 v112, v168, v108
	v_max_f32_e32 v108, 0, v111
	v_fmac_f32_e32 v120, v165, v108
	v_mfma_f32_16x16x32_bf16 v[72:75], v[28:31], v[76:79], v[72:75]
	v_max_f32_e32 v113, 0, v115
	v_fmac_f32_e32 v112, v169, v113
	v_add_f32_e32 v112, v120, v112
	v_mfma_f32_16x16x32_bf16 v[108:111], v[20:23], v[76:79], v[116:119]
	ds_write_b32 v99, v112 offset:1024
	s_nop 2
	v_max_f32_e32 v72, 0, v72
	v_fma_f32 v72, v174, v72, 0
	s_nop 1
	v_max_f32_e32 v76, 0, v108
	v_max_f32_e32 v73, 0, v73
	v_fma_f32 v76, v170, v76, 0
	v_max_f32_e32 v77, 0, v109
	v_fmac_f32_e32 v72, v175, v73
	v_fmac_f32_e32 v76, v171, v77
	v_max_f32_e32 v73, 0, v110
	v_fmac_f32_e32 v76, v172, v73
	v_max_f32_e32 v73, 0, v74
	v_fmac_f32_e32 v72, v176, v73
	v_max_f32_e32 v73, 0, v111
	v_fmac_f32_e32 v76, v173, v73
	v_max_f32_e32 v73, 0, v75
	v_fmac_f32_e32 v72, v177, v73
	v_add_f32_e32 v72, v76, v72
	v_add_u32_e32 v73, 0x10400, v99
	ds_write_b32 v73, v72
	s_waitcnt lgkmcnt(3)
	v_mfma_f32_16x16x32_bf16 v[72:75], v[0:3], v[40:43], 0
	v_mfma_f32_16x16x32_bf16 v[76:79], v[8:11], v[40:43], 0
	s_waitcnt lgkmcnt(2)
	v_mfma_f32_16x16x32_bf16 v[72:75], v[4:7], v[44:47], v[72:75]
	v_mfma_f32_16x16x32_bf16 v[76:79], v[12:15], v[44:47], v[76:79]
	v_mfma_f32_16x16x32_bf16 v[108:111], v[16:19], v[40:43], 0
	s_nop 5
	v_max_f32_e32 v72, 0, v72
	v_fma_f32 v112, v162, v72, 0
	v_max_f32_e32 v72, 0, v76
	v_fma_f32 v76, v166, v72, 0
	v_max_f32_e32 v72, 0, v73
	v_fmac_f32_e32 v112, v163, v72
	v_max_f32_e32 v72, 0, v77
	v_fmac_f32_e32 v76, v167, v72
	v_max_f32_e32 v72, 0, v74
	v_fmac_f32_e32 v112, v164, v72
	v_mfma_f32_16x16x32_bf16 v[40:43], v[24:27], v[40:43], 0
	v_max_f32_e32 v72, 0, v78
	v_fmac_f32_e32 v76, v168, v72
	v_max_f32_e32 v72, 0, v75
	v_fmac_f32_e32 v112, v165, v72
	v_mfma_f32_16x16x32_bf16 v[40:43], v[28:31], v[44:47], v[40:43]
	v_max_f32_e32 v77, 0, v79
	v_fmac_f32_e32 v76, v169, v77
	v_add_f32_e32 v76, v112, v76
	v_mfma_f32_16x16x32_bf16 v[72:75], v[20:23], v[44:47], v[108:111]
	ds_write_b32 v99, v76 offset:1088
	s_nop 2
	v_max_f32_e32 v40, 0, v40
	v_fma_f32 v40, v174, v40, 0
	s_nop 1
	v_max_f32_e32 v44, 0, v72
	v_max_f32_e32 v41, 0, v41
	v_fma_f32 v44, v170, v44, 0
	v_max_f32_e32 v45, 0, v73
	v_fmac_f32_e32 v40, v175, v41
	v_fmac_f32_e32 v44, v171, v45
	v_max_f32_e32 v41, 0, v74
	v_fmac_f32_e32 v44, v172, v41
	v_max_f32_e32 v41, 0, v42
	v_fmac_f32_e32 v40, v176, v41
	v_max_f32_e32 v41, 0, v75
	v_fmac_f32_e32 v44, v173, v41
	v_max_f32_e32 v41, 0, v43
	v_fmac_f32_e32 v40, v177, v41
	v_add_f32_e32 v40, v44, v40
	v_add_u32_e32 v41, 0x10440, v99
	ds_write_b32 v41, v40
.LBB0_822:
	s_add_i32 s57, s8, -1
	s_min_i32 s57, s57, s7
	s_waitcnt vmcnt(13)
	v_lshl_add_u32 v40, s57, 8, v102
	v_ashrrev_i32_e32 v41, 31, v40
	v_lshlrev_b64 v[40:41], 7, v[40:41]
	s_waitcnt vmcnt(12)
	v_lshl_add_u64 v[44:45], v[100:101], 0, v[40:41]
	global_load_dwordx4 v[72:75], v[44:45], off
	global_load_dwordx4 v[76:79], v[44:45], off offset:1024
	global_load_dwordx4 v[40:43], v[44:45], off offset:2048
	s_nop 0
	global_load_dwordx4 v[44:47], v[44:45], off offset:3072
	s_add_i32 s57, s8, -4
	s_cmp_ge_i32 s57, s6
	s_cbranch_scc1 .LBB0_824
	s_waitcnt vmcnt(15)
	ds_write_b128 v103, v[80:83]
	s_waitcnt vmcnt(14)
	ds_write_b128 v103, v[84:87] offset:1152
	ds_read_b128 v[80:83], v107
	ds_read_b128 v[84:87], v107 offset:64
	s_waitcnt vmcnt(13)
	ds_write_b128 v103, v[48:51]
	s_waitcnt vmcnt(12)
	ds_write_b128 v103, v[52:55] offset:1152
	ds_read_b128 v[48:51], v107
	ds_read_b128 v[52:55], v107 offset:64
	s_waitcnt lgkmcnt(5)
	v_mfma_f32_16x16x32_bf16 v[108:111], v[0:3], v[80:83], 0
	v_mfma_f32_16x16x32_bf16 v[112:115], v[8:11], v[80:83], 0
	s_waitcnt lgkmcnt(4)
	v_mfma_f32_16x16x32_bf16 v[108:111], v[4:7], v[84:87], v[108:111]
	v_mfma_f32_16x16x32_bf16 v[112:115], v[12:15], v[84:87], v[112:115]
	v_mfma_f32_16x16x32_bf16 v[116:119], v[16:19], v[80:83], 0
	s_nop 5
	v_max_f32_e32 v108, 0, v108
	v_fma_f32 v120, v162, v108, 0
	v_max_f32_e32 v108, 0, v109
	v_max_f32_e32 v112, 0, v112
	v_fmac_f32_e32 v120, v163, v108
	v_fma_f32 v112, v166, v112, 0
	v_max_f32_e32 v108, 0, v113
	v_fmac_f32_e32 v112, v167, v108
	v_max_f32_e32 v108, 0, v110
	v_fmac_f32_e32 v120, v164, v108
	v_mfma_f32_16x16x32_bf16 v[80:83], v[24:27], v[80:83], 0
	v_max_f32_e32 v108, 0, v114
	v_fmac_f32_e32 v112, v168, v108
	v_max_f32_e32 v108, 0, v111
	v_fmac_f32_e32 v120, v165, v108
	v_mfma_f32_16x16x32_bf16 v[80:83], v[28:31], v[84:87], v[80:83]
	v_max_f32_e32 v113, 0, v115
	v_fmac_f32_e32 v112, v169, v113
	v_add_f32_e32 v112, v120, v112
	v_mfma_f32_16x16x32_bf16 v[108:111], v[20:23], v[84:87], v[116:119]
	ds_write_b32 v99, v112 offset:2048
	s_nop 2
	v_max_f32_e32 v80, 0, v80
	v_fma_f32 v80, v174, v80, 0
	s_nop 1
	v_max_f32_e32 v84, 0, v108
	v_max_f32_e32 v81, 0, v81
	v_fma_f32 v84, v170, v84, 0
	v_max_f32_e32 v85, 0, v109
	v_fmac_f32_e32 v80, v175, v81
	v_fmac_f32_e32 v84, v171, v85
	v_max_f32_e32 v81, 0, v110
	v_fmac_f32_e32 v84, v172, v81
	v_max_f32_e32 v81, 0, v82
	v_fmac_f32_e32 v80, v176, v81
	v_max_f32_e32 v81, 0, v111
	v_fmac_f32_e32 v84, v173, v81
	v_max_f32_e32 v81, 0, v83
	v_fmac_f32_e32 v80, v177, v81
	v_add_f32_e32 v80, v84, v80
	v_add_u32_e32 v81, 0x10800, v99
	ds_write_b32 v81, v80
	s_waitcnt lgkmcnt(3)
	v_mfma_f32_16x16x32_bf16 v[80:83], v[0:3], v[48:51], 0
	v_mfma_f32_16x16x32_bf16 v[84:87], v[8:11], v[48:51], 0
	s_waitcnt lgkmcnt(2)
	v_mfma_f32_16x16x32_bf16 v[80:83], v[4:7], v[52:55], v[80:83]
	v_mfma_f32_16x16x32_bf16 v[84:87], v[12:15], v[52:55], v[84:87]
	v_mfma_f32_16x16x32_bf16 v[108:111], v[16:19], v[48:51], 0
	s_nop 5
	v_max_f32_e32 v80, 0, v80
	v_fma_f32 v112, v162, v80, 0
	v_max_f32_e32 v80, 0, v84
	v_fma_f32 v84, v166, v80, 0
	v_max_f32_e32 v80, 0, v81
	v_fmac_f32_e32 v112, v163, v80
	v_max_f32_e32 v80, 0, v85
	v_fmac_f32_e32 v84, v167, v80
	v_max_f32_e32 v80, 0, v82
	v_fmac_f32_e32 v112, v164, v80
	v_mfma_f32_16x16x32_bf16 v[48:51], v[24:27], v[48:51], 0
	v_max_f32_e32 v80, 0, v86
	v_fmac_f32_e32 v84, v168, v80
	v_max_f32_e32 v80, 0, v83
	v_fmac_f32_e32 v112, v165, v80
	v_mfma_f32_16x16x32_bf16 v[48:51], v[28:31], v[52:55], v[48:51]
	v_max_f32_e32 v85, 0, v87
	v_fmac_f32_e32 v84, v169, v85
	v_add_f32_e32 v84, v112, v84
	v_mfma_f32_16x16x32_bf16 v[80:83], v[20:23], v[52:55], v[108:111]
	ds_write_b32 v99, v84 offset:2112
	s_nop 2
	v_max_f32_e32 v48, 0, v48
	v_fma_f32 v48, v174, v48, 0
	s_nop 1
	v_max_f32_e32 v52, 0, v80
	v_max_f32_e32 v49, 0, v49
	v_fma_f32 v52, v170, v52, 0
	v_max_f32_e32 v53, 0, v81
	v_fmac_f32_e32 v48, v175, v49
	v_fmac_f32_e32 v52, v171, v53
	v_max_f32_e32 v49, 0, v82
	v_fmac_f32_e32 v52, v172, v49
	v_max_f32_e32 v49, 0, v50
	v_fmac_f32_e32 v48, v176, v49
	v_max_f32_e32 v49, 0, v83
	v_fmac_f32_e32 v52, v173, v49
	v_max_f32_e32 v49, 0, v51
	v_fmac_f32_e32 v48, v177, v49
	v_add_f32_e32 v48, v52, v48
	v_add_u32_e32 v49, 0x10840, v99
	ds_write_b32 v49, v48
.LBB0_824:
	s_min_i32 s57, s8, s7
	s_cmp_ge_i32 s40, s6
	s_waitcnt vmcnt(13)
	v_lshl_add_u32 v48, s57, 8, v102
	v_ashrrev_i32_e32 v49, 31, v48
	v_lshlrev_b64 v[48:49], 7, v[48:49]
	s_waitcnt vmcnt(12)
	v_lshl_add_u64 v[52:53], v[100:101], 0, v[48:49]
	global_load_dwordx4 v[80:83], v[52:53], off
	global_load_dwordx4 v[84:87], v[52:53], off offset:1024
	global_load_dwordx4 v[48:51], v[52:53], off offset:2048
	s_nop 0
	global_load_dwordx4 v[52:55], v[52:53], off offset:3072
	s_cbranch_scc1 .LBB0_819
	s_waitcnt vmcnt(15)
	ds_write_b128 v103, v[88:91]
	s_waitcnt vmcnt(14)
	ds_write_b128 v103, v[92:95] offset:1152
	ds_read_b128 v[88:91], v107
	ds_read_b128 v[92:95], v107 offset:64
	s_waitcnt vmcnt(13)
	ds_write_b128 v103, v[56:59]
	s_waitcnt vmcnt(12)
	ds_write_b128 v103, v[60:63] offset:1152
	ds_read_b128 v[56:59], v107
	ds_read_b128 v[60:63], v107 offset:64
	s_waitcnt lgkmcnt(5)
	v_mfma_f32_16x16x32_bf16 v[108:111], v[0:3], v[88:91], 0
	v_mfma_f32_16x16x32_bf16 v[112:115], v[8:11], v[88:91], 0
	s_waitcnt lgkmcnt(4)
	v_mfma_f32_16x16x32_bf16 v[108:111], v[4:7], v[92:95], v[108:111]
	v_mfma_f32_16x16x32_bf16 v[112:115], v[12:15], v[92:95], v[112:115]
	v_mfma_f32_16x16x32_bf16 v[116:119], v[16:19], v[88:91], 0
	s_nop 5
	v_max_f32_e32 v108, 0, v108
	v_fma_f32 v120, v162, v108, 0
	v_max_f32_e32 v108, 0, v109
	v_max_f32_e32 v112, 0, v112
	v_fmac_f32_e32 v120, v163, v108
	v_fma_f32 v112, v166, v112, 0
	v_max_f32_e32 v108, 0, v113
	v_fmac_f32_e32 v112, v167, v108
	v_max_f32_e32 v108, 0, v110
	v_fmac_f32_e32 v120, v164, v108
	v_mfma_f32_16x16x32_bf16 v[88:91], v[24:27], v[88:91], 0
	v_max_f32_e32 v108, 0, v114
	v_fmac_f32_e32 v112, v168, v108
	v_max_f32_e32 v108, 0, v111
	v_fmac_f32_e32 v120, v165, v108
	v_mfma_f32_16x16x32_bf16 v[88:91], v[28:31], v[92:95], v[88:91]
	v_max_f32_e32 v113, 0, v115
	v_fmac_f32_e32 v112, v169, v113
	v_add_f32_e32 v112, v120, v112
	v_mfma_f32_16x16x32_bf16 v[108:111], v[20:23], v[92:95], v[116:119]
	ds_write_b32 v99, v112 offset:3072
	s_nop 2
	v_max_f32_e32 v88, 0, v88
	v_fma_f32 v88, v174, v88, 0
	s_nop 1
	v_max_f32_e32 v92, 0, v108
	v_max_f32_e32 v89, 0, v89
	v_fma_f32 v92, v170, v92, 0
	v_max_f32_e32 v93, 0, v109
	v_fmac_f32_e32 v88, v175, v89
	v_fmac_f32_e32 v92, v171, v93
	v_max_f32_e32 v89, 0, v110
	v_fmac_f32_e32 v92, v172, v89
	v_max_f32_e32 v89, 0, v90
	v_fmac_f32_e32 v88, v176, v89
	v_max_f32_e32 v89, 0, v111
	v_fmac_f32_e32 v92, v173, v89
	v_max_f32_e32 v89, 0, v91
	v_fmac_f32_e32 v88, v177, v89
	v_add_f32_e32 v88, v92, v88
	v_add_u32_e32 v89, 0x10c00, v99
	ds_write_b32 v89, v88
	s_waitcnt lgkmcnt(3)
	v_mfma_f32_16x16x32_bf16 v[88:91], v[0:3], v[56:59], 0
	v_mfma_f32_16x16x32_bf16 v[92:95], v[8:11], v[56:59], 0
	s_waitcnt lgkmcnt(2)
	v_mfma_f32_16x16x32_bf16 v[88:91], v[4:7], v[60:63], v[88:91]
	v_mfma_f32_16x16x32_bf16 v[92:95], v[12:15], v[60:63], v[92:95]
	v_mfma_f32_16x16x32_bf16 v[108:111], v[16:19], v[56:59], 0
	s_nop 5
	v_max_f32_e32 v88, 0, v88
	v_fma_f32 v103, v162, v88, 0
	v_max_f32_e32 v88, 0, v92
	v_fma_f32 v92, v166, v88, 0
	v_max_f32_e32 v88, 0, v89
	v_fmac_f32_e32 v103, v163, v88
	v_max_f32_e32 v88, 0, v93
	v_fmac_f32_e32 v92, v167, v88
	v_max_f32_e32 v88, 0, v90
	v_fmac_f32_e32 v103, v164, v88
	v_mfma_f32_16x16x32_bf16 v[56:59], v[24:27], v[56:59], 0
	v_max_f32_e32 v88, 0, v94
	v_fmac_f32_e32 v92, v168, v88
	v_max_f32_e32 v88, 0, v91
	v_fmac_f32_e32 v103, v165, v88
	v_mfma_f32_16x16x32_bf16 v[56:59], v[28:31], v[60:63], v[56:59]
	v_max_f32_e32 v93, 0, v95
	v_fmac_f32_e32 v92, v169, v93
	v_add_f32_e32 v92, v103, v92
	v_mfma_f32_16x16x32_bf16 v[88:91], v[20:23], v[60:63], v[108:111]
	ds_write_b32 v99, v92 offset:3136
	s_nop 2
	v_max_f32_e32 v56, 0, v56
	v_fma_f32 v56, v174, v56, 0
	s_nop 1
	v_max_f32_e32 v60, 0, v88
	v_max_f32_e32 v57, 0, v57
	v_fma_f32 v60, v170, v60, 0
	v_max_f32_e32 v61, 0, v89
	v_fmac_f32_e32 v56, v175, v57
	v_fmac_f32_e32 v60, v171, v61
	v_max_f32_e32 v57, 0, v90
	v_fmac_f32_e32 v60, v172, v57
	v_max_f32_e32 v57, 0, v58
	v_fmac_f32_e32 v56, v176, v57
	v_max_f32_e32 v57, 0, v91
	v_fmac_f32_e32 v60, v173, v57
	v_max_f32_e32 v57, 0, v59
	v_fmac_f32_e32 v56, v177, v57
	v_add_f32_e32 v56, v60, v56
	v_add_u32_e32 v57, 0x10c40, v99
	ds_write_b32 v57, v56
	s_branch .LBB0_819

.LBB0_834:
	s_add_i32 s40, s8, -3
	s_min_i32 s9, s40, s7
	s_waitcnt vmcnt(13)
	v_lshl_add_u32 v56, s9, 8, v102
	v_ashrrev_i32_e32 v57, 31, v56
	v_lshlrev_b64 v[56:57], 7, v[56:57]
	s_waitcnt vmcnt(12)
	v_lshl_add_u64 v[60:61], v[100:101], 0, v[56:57]
	global_load_dwordx4 v[88:91], v[60:61], off
	global_load_dwordx4 v[92:95], v[60:61], off offset:1024
	global_load_dwordx4 v[56:59], v[60:61], off offset:2048
	s_nop 0
	global_load_dwordx4 v[60:63], v[60:61], off offset:3072
	v_add_u32_e32 v103, v178, v98
	s_waitcnt vmcnt(15)
	ds_write_b128 v103, v[64:67]
	s_waitcnt vmcnt(14)
	ds_write_b128 v103, v[68:71] offset:1152
	v_add_u32_e32 v191, v179, v96
	ds_read_b128 v[64:67], v191
	ds_read_b128 v[68:71], v191 offset:64
	s_waitcnt vmcnt(13)
	ds_write_b128 v103, v[32:35]
	s_waitcnt vmcnt(12)
	ds_write_b128 v103, v[36:39] offset:1152
	ds_read_b128 v[32:35], v191
	ds_read_b128 v[36:39], v191 offset:64
	s_waitcnt lgkmcnt(5)
	v_mfma_f32_16x16x32_bf16 v[196:199], v[0:3], v[64:67], 0
	v_mfma_f32_16x16x32_bf16 v[200:203], v[8:11], v[64:67], 0
	s_waitcnt lgkmcnt(4)
	v_mfma_f32_16x16x32_bf16 v[196:199], v[4:7], v[68:71], v[196:199]
	v_mfma_f32_16x16x32_bf16 v[200:203], v[12:15], v[68:71], v[200:203]
	v_mfma_f32_16x16x32_bf16 v[204:207], v[16:19], v[64:67], 0
	s_nop 5
	v_max_f32_e32 v192, 0, v196
	v_fma_f32 v192, v162, v192, 0
	v_max_f32_e32 v195, 0, v197
	v_max_f32_e32 v193, 0, v200
	v_fmac_f32_e32 v192, v163, v195
	v_fma_f32 v193, v166, v193, 0
	v_max_f32_e32 v195, 0, v201
	v_mfma_f32_16x16x32_bf16 v[64:67], v[24:27], v[64:67], 0
	v_fmac_f32_e32 v193, v167, v195
	v_max_f32_e32 v195, 0, v198
	v_fmac_f32_e32 v192, v164, v195
	v_max_f32_e32 v195, 0, v202
	v_mfma_f32_16x16x32_bf16 v[64:67], v[28:31], v[68:71], v[64:67]
	v_fmac_f32_e32 v193, v168, v195
	v_max_f32_e32 v195, 0, v199
	v_mfma_f32_16x16x32_bf16 v[196:199], v[20:23], v[68:71], v[204:207]
	v_fmac_f32_e32 v192, v165, v195
	s_nop 2
	s_nop 0
	v_max_f32_e32 v64, 0, v64
	v_fma_f32 v64, v174, v64, 0
	s_nop 0
	v_max_f32_e32 v68, 0, v196
	v_max_f32_e32 v65, 0, v65
	v_fma_f32 v68, v170, v68, 0
	v_max_f32_e32 v69, 0, v197
	v_fmac_f32_e32 v64, v175, v65
	v_fmac_f32_e32 v68, v171, v69
	v_max_f32_e32 v65, 0, v198
	v_fmac_f32_e32 v68, v172, v65
	v_max_f32_e32 v65, 0, v66
	v_fmac_f32_e32 v64, v176, v65
	v_max_f32_e32 v65, 0, v199
	v_fmac_f32_e32 v68, v173, v65
	v_max_f32_e32 v195, 0, v203
	v_max_f32_e32 v65, 0, v67
	v_fmac_f32_e32 v193, v169, v195
	v_fmac_f32_e32 v64, v177, v65
	v_add_f32_e32 v192, v192, v193
	v_add_f32_e32 v64, v68, v64
	v_add_u32_e32 v65, 0x10000, v180
	ds_write_b32 v180, v192
	ds_write_b32 v65, v64
	s_waitcnt lgkmcnt(3)
	v_mfma_f32_16x16x32_bf16 v[64:67], v[0:3], v[32:35], 0
	v_mfma_f32_16x16x32_bf16 v[68:71], v[8:11], v[32:35], 0
	s_waitcnt lgkmcnt(2)
	v_mfma_f32_16x16x32_bf16 v[64:67], v[4:7], v[36:39], v[64:67]
	v_mfma_f32_16x16x32_bf16 v[68:71], v[12:15], v[36:39], v[68:71]
	v_mfma_f32_16x16x32_bf16 v[196:199], v[16:19], v[32:35], 0
	s_nop 5
	v_max_f32_e32 v64, 0, v64
	v_fma_f32 v192, v162, v64, 0
	v_max_f32_e32 v64, 0, v68
	v_fma_f32 v68, v166, v64, 0
	v_max_f32_e32 v64, 0, v65
	v_fmac_f32_e32 v192, v163, v64
	v_max_f32_e32 v64, 0, v69
	v_fmac_f32_e32 v68, v167, v64
	v_max_f32_e32 v64, 0, v66
	v_fmac_f32_e32 v192, v164, v64
	v_mfma_f32_16x16x32_bf16 v[32:35], v[24:27], v[32:35], 0
	v_max_f32_e32 v64, 0, v70
	v_fmac_f32_e32 v68, v168, v64
	v_max_f32_e32 v64, 0, v67
	v_fmac_f32_e32 v192, v165, v64
	v_mfma_f32_16x16x32_bf16 v[32:35], v[28:31], v[36:39], v[32:35]
	v_max_f32_e32 v69, 0, v71
	v_fmac_f32_e32 v68, v169, v69
	v_add_f32_e32 v68, v192, v68
	v_mfma_f32_16x16x32_bf16 v[64:67], v[20:23], v[36:39], v[196:199]
	ds_write_b32 v180, v68 offset:64
	s_nop 2
	v_max_f32_e32 v32, 0, v32
	v_fma_f32 v32, v174, v32, 0
	s_nop 1
	v_max_f32_e32 v36, 0, v64
	v_max_f32_e32 v33, 0, v33
	v_fma_f32 v36, v170, v36, 0
	v_max_f32_e32 v37, 0, v65
	v_fmac_f32_e32 v32, v175, v33
	v_fmac_f32_e32 v36, v171, v37
	v_max_f32_e32 v33, 0, v66
	v_fmac_f32_e32 v36, v172, v33
	v_max_f32_e32 v33, 0, v34
	v_fmac_f32_e32 v32, v176, v33
	v_max_f32_e32 v33, 0, v67
	v_fmac_f32_e32 v36, v173, v33
	v_max_f32_e32 v33, 0, v35
	v_fmac_f32_e32 v32, v177, v33
	v_add_f32_e32 v32, v36, v32
	v_add_u32_e32 v33, 0x10040, v180
	ds_write_b32 v33, v32
	s_add_i32 s9, s8, -2
	s_min_i32 s57, s9, s7
	v_lshl_add_u32 v32, s57, 8, v102
	v_ashrrev_i32_e32 v33, 31, v32
	v_lshlrev_b64 v[32:33], 7, v[32:33]
	v_lshl_add_u64 v[36:37], v[100:101], 0, v[32:33]
	global_load_dwordx4 v[64:67], v[36:37], off
	global_load_dwordx4 v[68:71], v[36:37], off offset:1024
	global_load_dwordx4 v[32:35], v[36:37], off offset:2048
	s_nop 0
	global_load_dwordx4 v[36:39], v[36:37], off offset:3072
	s_add_i32 s57, s8, -5
	s_cmp_ge_i32 s57, s6
	s_cbranch_scc1 .LBB0_836
	s_waitcnt vmcnt(15)
	ds_write_b128 v103, v[72:75]
	s_waitcnt vmcnt(14)
	ds_write_b128 v103, v[76:79] offset:1152
	ds_read_b128 v[72:75], v191
	ds_read_b128 v[76:79], v191 offset:64
	s_waitcnt vmcnt(13)
	ds_write_b128 v103, v[40:43]
	s_waitcnt vmcnt(12)
	ds_write_b128 v103, v[44:47] offset:1152
	ds_read_b128 v[40:43], v191
	ds_read_b128 v[44:47], v191 offset:64
	s_waitcnt lgkmcnt(5)
	v_mfma_f32_16x16x32_bf16 v[196:199], v[0:3], v[72:75], 0
	v_mfma_f32_16x16x32_bf16 v[200:203], v[8:11], v[72:75], 0
	s_waitcnt lgkmcnt(4)
	v_mfma_f32_16x16x32_bf16 v[196:199], v[4:7], v[76:79], v[196:199]
	v_mfma_f32_16x16x32_bf16 v[200:203], v[12:15], v[76:79], v[200:203]
	v_mfma_f32_16x16x32_bf16 v[204:207], v[16:19], v[72:75], 0
	s_nop 5
	v_max_f32_e32 v192, 0, v196
	v_fma_f32 v192, v162, v192, 0
	v_max_f32_e32 v195, 0, v197
	v_max_f32_e32 v193, 0, v200
	v_fmac_f32_e32 v192, v163, v195
	v_fma_f32 v193, v166, v193, 0
	v_max_f32_e32 v195, 0, v201
	v_mfma_f32_16x16x32_bf16 v[72:75], v[24:27], v[72:75], 0
	v_fmac_f32_e32 v193, v167, v195
	v_max_f32_e32 v195, 0, v198
	v_fmac_f32_e32 v192, v164, v195
	v_max_f32_e32 v195, 0, v202
	v_mfma_f32_16x16x32_bf16 v[72:75], v[28:31], v[76:79], v[72:75]
	v_fmac_f32_e32 v193, v168, v195
	v_max_f32_e32 v195, 0, v199
	v_mfma_f32_16x16x32_bf16 v[196:199], v[20:23], v[76:79], v[204:207]
	v_fmac_f32_e32 v192, v165, v195
	s_nop 2
	s_nop 0
	v_max_f32_e32 v72, 0, v72
	v_fma_f32 v72, v174, v72, 0
	s_nop 0
	v_max_f32_e32 v76, 0, v196
	v_max_f32_e32 v73, 0, v73
	v_fma_f32 v76, v170, v76, 0
	v_max_f32_e32 v77, 0, v197
	v_fmac_f32_e32 v72, v175, v73
	v_fmac_f32_e32 v76, v171, v77
	v_max_f32_e32 v73, 0, v198
	v_fmac_f32_e32 v76, v172, v73
	v_max_f32_e32 v73, 0, v74
	v_fmac_f32_e32 v72, v176, v73
	v_max_f32_e32 v73, 0, v199
	v_fmac_f32_e32 v76, v173, v73
	v_max_f32_e32 v195, 0, v203
	v_max_f32_e32 v73, 0, v75
	v_fmac_f32_e32 v193, v169, v195
	v_fmac_f32_e32 v72, v177, v73
	v_add_f32_e32 v192, v192, v193
	v_add_f32_e32 v72, v76, v72
	v_add_u32_e32 v73, 0x10400, v180
	ds_write_b32 v180, v192 offset:1024
	ds_write_b32 v73, v72
	s_waitcnt lgkmcnt(3)
	v_mfma_f32_16x16x32_bf16 v[72:75], v[0:3], v[40:43], 0
	v_mfma_f32_16x16x32_bf16 v[76:79], v[8:11], v[40:43], 0
	s_waitcnt lgkmcnt(2)
	v_mfma_f32_16x16x32_bf16 v[72:75], v[4:7], v[44:47], v[72:75]
	v_mfma_f32_16x16x32_bf16 v[76:79], v[12:15], v[44:47], v[76:79]
	v_mfma_f32_16x16x32_bf16 v[196:199], v[16:19], v[40:43], 0
	s_nop 5
	v_max_f32_e32 v72, 0, v72
	v_fma_f32 v192, v162, v72, 0
	v_max_f32_e32 v72, 0, v76
	v_fma_f32 v76, v166, v72, 0
	v_max_f32_e32 v72, 0, v73
	v_fmac_f32_e32 v192, v163, v72
	v_max_f32_e32 v72, 0, v77
	v_fmac_f32_e32 v76, v167, v72
	v_max_f32_e32 v72, 0, v74
	v_fmac_f32_e32 v192, v164, v72
	v_mfma_f32_16x16x32_bf16 v[40:43], v[24:27], v[40:43], 0
	v_max_f32_e32 v72, 0, v78
	v_fmac_f32_e32 v76, v168, v72
	v_max_f32_e32 v72, 0, v75
	v_fmac_f32_e32 v192, v165, v72
	v_mfma_f32_16x16x32_bf16 v[40:43], v[28:31], v[44:47], v[40:43]
	v_max_f32_e32 v77, 0, v79
	v_fmac_f32_e32 v76, v169, v77
	v_add_f32_e32 v76, v192, v76
	v_mfma_f32_16x16x32_bf16 v[72:75], v[20:23], v[44:47], v[196:199]
	ds_write_b32 v180, v76 offset:1088
	s_nop 2
	v_max_f32_e32 v40, 0, v40
	v_fma_f32 v40, v174, v40, 0
	s_nop 1
	v_max_f32_e32 v44, 0, v72
	v_max_f32_e32 v41, 0, v41
	v_fma_f32 v44, v170, v44, 0
	v_max_f32_e32 v45, 0, v73
	v_fmac_f32_e32 v40, v175, v41
	v_fmac_f32_e32 v44, v171, v45
	v_max_f32_e32 v41, 0, v74
	v_fmac_f32_e32 v44, v172, v41
	v_max_f32_e32 v41, 0, v42
	v_fmac_f32_e32 v40, v176, v41
	v_max_f32_e32 v41, 0, v75
	v_fmac_f32_e32 v44, v173, v41
	v_max_f32_e32 v41, 0, v43
	v_fmac_f32_e32 v40, v177, v41
	v_add_f32_e32 v40, v44, v40
	v_add_u32_e32 v41, 0x10440, v180
	ds_write_b32 v41, v40
.LBB0_836:
	s_add_i32 s57, s8, -1
	s_min_i32 s57, s57, s7
	s_waitcnt vmcnt(13)
	v_lshl_add_u32 v40, s57, 8, v102
	v_ashrrev_i32_e32 v41, 31, v40
	v_lshlrev_b64 v[40:41], 7, v[40:41]
	s_waitcnt vmcnt(12)
	v_lshl_add_u64 v[44:45], v[100:101], 0, v[40:41]
	global_load_dwordx4 v[72:75], v[44:45], off
	global_load_dwordx4 v[76:79], v[44:45], off offset:1024
	global_load_dwordx4 v[40:43], v[44:45], off offset:2048
	s_nop 0
	global_load_dwordx4 v[44:47], v[44:45], off offset:3072
	s_add_i32 s57, s8, -4
	s_cmp_ge_i32 s57, s6
	s_cbranch_scc1 .LBB0_838
	s_waitcnt vmcnt(15)
	ds_write_b128 v103, v[80:83]
	s_waitcnt vmcnt(14)
	ds_write_b128 v103, v[84:87] offset:1152
	ds_read_b128 v[80:83], v191
	ds_read_b128 v[84:87], v191 offset:64
	s_waitcnt vmcnt(13)
	ds_write_b128 v103, v[48:51]
	s_waitcnt vmcnt(12)
	ds_write_b128 v103, v[52:55] offset:1152
	ds_read_b128 v[48:51], v191
	ds_read_b128 v[52:55], v191 offset:64
	s_waitcnt lgkmcnt(5)
	v_mfma_f32_16x16x32_bf16 v[196:199], v[0:3], v[80:83], 0
	v_mfma_f32_16x16x32_bf16 v[200:203], v[8:11], v[80:83], 0
	s_waitcnt lgkmcnt(4)
	v_mfma_f32_16x16x32_bf16 v[196:199], v[4:7], v[84:87], v[196:199]
	v_mfma_f32_16x16x32_bf16 v[200:203], v[12:15], v[84:87], v[200:203]
	v_mfma_f32_16x16x32_bf16 v[204:207], v[16:19], v[80:83], 0
	s_nop 5
	v_max_f32_e32 v192, 0, v196
	v_fma_f32 v192, v162, v192, 0
	v_max_f32_e32 v195, 0, v197
	v_max_f32_e32 v193, 0, v200
	v_fmac_f32_e32 v192, v163, v195
	v_fma_f32 v193, v166, v193, 0
	v_max_f32_e32 v195, 0, v201
	v_mfma_f32_16x16x32_bf16 v[80:83], v[24:27], v[80:83], 0
	v_fmac_f32_e32 v193, v167, v195
	v_max_f32_e32 v195, 0, v198
	v_fmac_f32_e32 v192, v164, v195
	v_max_f32_e32 v195, 0, v202
	v_mfma_f32_16x16x32_bf16 v[80:83], v[28:31], v[84:87], v[80:83]
	v_fmac_f32_e32 v193, v168, v195
	v_max_f32_e32 v195, 0, v199
	v_mfma_f32_16x16x32_bf16 v[196:199], v[20:23], v[84:87], v[204:207]
	v_fmac_f32_e32 v192, v165, v195
	s_nop 2
	s_nop 0
	v_max_f32_e32 v80, 0, v80
	v_fma_f32 v80, v174, v80, 0
	s_nop 0
	v_max_f32_e32 v84, 0, v196
	v_max_f32_e32 v81, 0, v81
	v_fma_f32 v84, v170, v84, 0
	v_max_f32_e32 v85, 0, v197
	v_fmac_f32_e32 v80, v175, v81
	v_fmac_f32_e32 v84, v171, v85
	v_max_f32_e32 v81, 0, v198
	v_fmac_f32_e32 v84, v172, v81
	v_max_f32_e32 v81, 0, v82
	v_fmac_f32_e32 v80, v176, v81
	v_max_f32_e32 v81, 0, v199
	v_fmac_f32_e32 v84, v173, v81
	v_max_f32_e32 v195, 0, v203
	v_max_f32_e32 v81, 0, v83
	v_fmac_f32_e32 v193, v169, v195
	v_fmac_f32_e32 v80, v177, v81
	v_add_f32_e32 v192, v192, v193
	v_add_f32_e32 v80, v84, v80
	v_add_u32_e32 v81, 0x10800, v180
	ds_write_b32 v180, v192 offset:2048
	ds_write_b32 v81, v80
	s_waitcnt lgkmcnt(3)
	v_mfma_f32_16x16x32_bf16 v[80:83], v[0:3], v[48:51], 0
	v_mfma_f32_16x16x32_bf16 v[84:87], v[8:11], v[48:51], 0
	s_waitcnt lgkmcnt(2)
	v_mfma_f32_16x16x32_bf16 v[80:83], v[4:7], v[52:55], v[80:83]
	v_mfma_f32_16x16x32_bf16 v[84:87], v[12:15], v[52:55], v[84:87]
	v_mfma_f32_16x16x32_bf16 v[196:199], v[16:19], v[48:51], 0
	s_nop 5
	v_max_f32_e32 v80, 0, v80
	v_fma_f32 v192, v162, v80, 0
	v_max_f32_e32 v80, 0, v84
	v_fma_f32 v84, v166, v80, 0
	v_max_f32_e32 v80, 0, v81
	v_fmac_f32_e32 v192, v163, v80
	v_max_f32_e32 v80, 0, v85
	v_fmac_f32_e32 v84, v167, v80
	v_max_f32_e32 v80, 0, v82
	v_fmac_f32_e32 v192, v164, v80
	v_mfma_f32_16x16x32_bf16 v[48:51], v[24:27], v[48:51], 0
	v_max_f32_e32 v80, 0, v86
	v_fmac_f32_e32 v84, v168, v80
	v_max_f32_e32 v80, 0, v83
	v_fmac_f32_e32 v192, v165, v80
	v_mfma_f32_16x16x32_bf16 v[48:51], v[28:31], v[52:55], v[48:51]
	v_max_f32_e32 v85, 0, v87
	v_fmac_f32_e32 v84, v169, v85
	v_add_f32_e32 v84, v192, v84
	v_mfma_f32_16x16x32_bf16 v[80:83], v[20:23], v[52:55], v[196:199]
	ds_write_b32 v180, v84 offset:2112
	s_nop 2
	v_max_f32_e32 v48, 0, v48
	v_fma_f32 v48, v174, v48, 0
	s_nop 1
	v_max_f32_e32 v52, 0, v80
	v_max_f32_e32 v49, 0, v49
	v_fma_f32 v52, v170, v52, 0
	v_max_f32_e32 v53, 0, v81
	v_fmac_f32_e32 v48, v175, v49
	v_fmac_f32_e32 v52, v171, v53
	v_max_f32_e32 v49, 0, v82
	v_fmac_f32_e32 v52, v172, v49
	v_max_f32_e32 v49, 0, v50
	v_fmac_f32_e32 v48, v176, v49
	v_max_f32_e32 v49, 0, v83
	v_fmac_f32_e32 v52, v173, v49
	v_max_f32_e32 v49, 0, v51
	v_fmac_f32_e32 v48, v177, v49
	v_add_f32_e32 v48, v52, v48
	v_add_u32_e32 v49, 0x10840, v180
	ds_write_b32 v49, v48
.LBB0_838:
	s_min_i32 s57, s8, s7
	s_cmp_ge_i32 s40, s6
	s_waitcnt vmcnt(13)
	v_lshl_add_u32 v48, s57, 8, v102
	v_ashrrev_i32_e32 v49, 31, v48
	v_lshlrev_b64 v[48:49], 7, v[48:49]
	s_waitcnt vmcnt(12)
	v_lshl_add_u64 v[52:53], v[100:101], 0, v[48:49]
	global_load_dwordx4 v[80:83], v[52:53], off
	global_load_dwordx4 v[84:87], v[52:53], off offset:1024
	global_load_dwordx4 v[48:51], v[52:53], off offset:2048
	s_nop 0
	global_load_dwordx4 v[52:55], v[52:53], off offset:3072
	s_cbranch_scc1 .LBB0_833
	s_waitcnt vmcnt(15)
	ds_write_b128 v103, v[88:91]
	s_waitcnt vmcnt(14)
	ds_write_b128 v103, v[92:95] offset:1152
	ds_read_b128 v[88:91], v191
	ds_read_b128 v[92:95], v191 offset:64
	s_waitcnt vmcnt(13)
	ds_write_b128 v103, v[56:59]
	s_waitcnt vmcnt(12)
	ds_write_b128 v103, v[60:63] offset:1152
	ds_read_b128 v[56:59], v191
	ds_read_b128 v[60:63], v191 offset:64
	s_waitcnt lgkmcnt(5)
	v_mfma_f32_16x16x32_bf16 v[196:199], v[0:3], v[88:91], 0
	v_mfma_f32_16x16x32_bf16 v[200:203], v[8:11], v[88:91], 0
	s_waitcnt lgkmcnt(4)
	v_mfma_f32_16x16x32_bf16 v[196:199], v[4:7], v[92:95], v[196:199]
	v_mfma_f32_16x16x32_bf16 v[200:203], v[12:15], v[92:95], v[200:203]
	v_mfma_f32_16x16x32_bf16 v[204:207], v[16:19], v[88:91], 0
	s_nop 5
	v_max_f32_e32 v192, 0, v196
	v_fma_f32 v192, v162, v192, 0
	v_max_f32_e32 v195, 0, v197
	v_max_f32_e32 v193, 0, v200
	v_fmac_f32_e32 v192, v163, v195
	v_fma_f32 v193, v166, v193, 0
	v_max_f32_e32 v195, 0, v201
	v_mfma_f32_16x16x32_bf16 v[88:91], v[24:27], v[88:91], 0
	v_fmac_f32_e32 v193, v167, v195
	v_max_f32_e32 v195, 0, v198
	v_fmac_f32_e32 v192, v164, v195
	v_max_f32_e32 v195, 0, v202
	v_mfma_f32_16x16x32_bf16 v[88:91], v[28:31], v[92:95], v[88:91]
	v_fmac_f32_e32 v193, v168, v195
	v_max_f32_e32 v195, 0, v199
	v_mfma_f32_16x16x32_bf16 v[196:199], v[20:23], v[92:95], v[204:207]
	v_fmac_f32_e32 v192, v165, v195
	s_nop 2
	s_nop 0
	v_max_f32_e32 v88, 0, v88
	v_fma_f32 v88, v174, v88, 0
	s_nop 0
	v_max_f32_e32 v92, 0, v196
	v_max_f32_e32 v89, 0, v89
	v_fma_f32 v92, v170, v92, 0
	v_max_f32_e32 v93, 0, v197
	v_fmac_f32_e32 v88, v175, v89
	v_fmac_f32_e32 v92, v171, v93
	v_max_f32_e32 v89, 0, v198
	v_fmac_f32_e32 v92, v172, v89
	v_max_f32_e32 v89, 0, v90
	v_fmac_f32_e32 v88, v176, v89
	v_max_f32_e32 v89, 0, v199
	v_fmac_f32_e32 v92, v173, v89
	v_max_f32_e32 v195, 0, v203
	v_max_f32_e32 v89, 0, v91
	v_fmac_f32_e32 v193, v169, v195
	v_fmac_f32_e32 v88, v177, v89
	v_add_f32_e32 v192, v192, v193
	v_add_f32_e32 v88, v92, v88
	v_add_u32_e32 v89, 0x10c00, v180
	ds_write_b32 v180, v192 offset:3072
	ds_write_b32 v89, v88
	s_waitcnt lgkmcnt(3)
	v_mfma_f32_16x16x32_bf16 v[88:91], v[0:3], v[56:59], 0
	v_mfma_f32_16x16x32_bf16 v[92:95], v[8:11], v[56:59], 0
	s_waitcnt lgkmcnt(2)
	v_mfma_f32_16x16x32_bf16 v[88:91], v[4:7], v[60:63], v[88:91]
	v_mfma_f32_16x16x32_bf16 v[92:95], v[12:15], v[60:63], v[92:95]
	v_mfma_f32_16x16x32_bf16 v[196:199], v[16:19], v[56:59], 0
	s_nop 5
	v_max_f32_e32 v88, 0, v88
	v_fma_f32 v103, v162, v88, 0
	v_max_f32_e32 v88, 0, v92
	v_fma_f32 v92, v166, v88, 0
	v_max_f32_e32 v88, 0, v89
	v_fmac_f32_e32 v103, v163, v88
	v_max_f32_e32 v88, 0, v93
	v_fmac_f32_e32 v92, v167, v88
	v_max_f32_e32 v88, 0, v90
	v_fmac_f32_e32 v103, v164, v88
	v_mfma_f32_16x16x32_bf16 v[56:59], v[24:27], v[56:59], 0
	v_max_f32_e32 v88, 0, v94
	v_fmac_f32_e32 v92, v168, v88
	v_max_f32_e32 v88, 0, v91
	v_fmac_f32_e32 v103, v165, v88
	v_mfma_f32_16x16x32_bf16 v[56:59], v[28:31], v[60:63], v[56:59]
	v_max_f32_e32 v93, 0, v95
	v_fmac_f32_e32 v92, v169, v93
	v_add_f32_e32 v92, v103, v92
	v_mfma_f32_16x16x32_bf16 v[88:91], v[20:23], v[60:63], v[196:199]
	ds_write_b32 v180, v92 offset:3136
	s_nop 2
	v_max_f32_e32 v56, 0, v56
	v_fma_f32 v56, v174, v56, 0
	s_nop 1
	v_max_f32_e32 v60, 0, v88
	v_max_f32_e32 v57, 0, v57
	v_fma_f32 v60, v170, v60, 0
	v_max_f32_e32 v61, 0, v89
	v_fmac_f32_e32 v56, v175, v57
	v_fmac_f32_e32 v60, v171, v61
	v_max_f32_e32 v57, 0, v90
	v_fmac_f32_e32 v60, v172, v57
	v_max_f32_e32 v57, 0, v58
	v_fmac_f32_e32 v56, v176, v57
	v_max_f32_e32 v57, 0, v91
	v_fmac_f32_e32 v60, v173, v57
	v_max_f32_e32 v57, 0, v59
	v_fmac_f32_e32 v56, v177, v57
	v_add_f32_e32 v56, v60, v56
	v_add_u32_e32 v57, 0x10c40, v180
	ds_write_b32 v57, v56
	s_branch .LBB0_833
